# v23 + counted vmcnt waits at each residual/activation load's first use in the EpiRes (w_out, ff2) and EpiGlu epilogues instead of one vmcnt(0) per load batch
# baseline (speedup 1.0000x reference)
; __device__ __forceinline__ float shx(float v, int lane, int o) { return __int_as_float(__builtin_amdgcn_ds_bpermute((lane ^ o) << 2, __float_as_int(v))); }
; __device__ __forceinline__ u32x4 pack8(const f32x4 a, const f32x4 b) { u32x4 w; w.x = cvt_pk_bf16(a[0], a[1]); w.y = cvt_pk_bf16(a[2], a[3]); w.z = cvt_pk_bf16(b[0], b[1]); w.w = cvt_pk_bf16(b[2], b[3]); return w; }
; __device__ __forceinline__ void unpack8(const u32x4 w, f32x4& a, f32x4& b) { a = (f32x4){bflo(w.x), bfhi(w.x), bflo(w.y), bfhi(w.y)}; b = (f32x4){bflo(w.z), bfhi(w.z), bflo(w.w), bfhi(w.w)}; }
;     __device__ __forceinline__ void operator()(const Acc& acc, const Unit& u, int wr, int wc, int fr, int fq) const {
;     ...
; #pragma unroll
;         for (int ai = 0; ai < 2; ++ai) {
;             u32x4 hv[4][2];
; #pragma unroll
;             for (int m = 0; m < 4; ++m)
; #pragma unroll
;                 for (int bj = 0; bj < 2; ++bj) hv[m][bj] = *(const u32x4*)(hb + (size_t)(row0 + ai * 128 + m * 16) * DM + col0 + bj * 128);
; #pragma unroll
;             for (int m = 0; m < 4; ++m) { const size_t row = (size_t)(row0 + ai * 128 + m * 16); float sq = 0.f;
; #pragma unroll
;                 for (int bj = 0; bj < 2; ++bj) { f32x4 o0, o1; unpack8(hv[m][bj], o0, o1); o0 += acc[ai][bj][m][0] * sc; o1 += acc[ai][bj][m][1] * sc;
;                     *(u32x4*)(hb + row * DM + col0 + bj * 128) = pack8(o0, o1);
;                     sq += ((o0[0] * o0[0] + o0[1] * o0[1]) + (o0[2] * o0[2] + o0[3] * o0[3])) + ((o1[0] * o1[0] + o1[1] * o1[1]) + (o1[2] * o1[2] + o1[3] * o1[3])); }
;                 const int lane = fq * 16 + fr; sq += shx(sq, lane, 16); sq += shx(sq, lane, 32);
;                 if (fq == 0) ssq[row * 16 + u.pn * 4 + wc] = sq; } }
.LBB0_66:
.LBB0_67:
	v_lshl_add_u32 v172, s30, 8, v130
	v_lshlrev_b32_e32 v130, 2, v133
	v_lshlrev_b64 v[202:203], 1, v[168:169]
	v_ashrrev_i32_e32 v173, 31, v172
	v_lshl_add_u32 v130, v132, 6, v130
	v_lshl_add_u64 v[170:171], s[36:37], 0, v[202:203]
	v_lshlrev_b64 v[204:205], 11, v[172:173]
	v_xor_b32_e32 v191, 64, v130
	v_xor_b32_e32 v190, 0x80, v130
	v_lshl_add_u64 v[130:131], v[170:171], 0, v[204:205]
	global_load_dwordx4 v[192:195], v[130:131], off
	global_load_dwordx4 v[154:157], v[130:131], off offset:256
	v_add_u32_e32 v182, 16, v172
	v_ashrrev_i32_e32 v183, 31, v182
	v_add_u32_e32 v178, 32, v172
	v_lshlrev_b64 v[184:185], 11, v[182:183]
	v_ashrrev_i32_e32 v179, 31, v178
	v_add_u32_e32 v174, 48, v172
	v_lshl_add_u64 v[130:131], v[170:171], 0, v[184:185]
	v_lshlrev_b64 v[180:181], 11, v[178:179]
	v_ashrrev_i32_e32 v175, 31, v174
	global_load_dwordx4 v[150:153], v[130:131], off
	global_load_dwordx4 v[146:149], v[130:131], off offset:256
	v_lshl_add_u64 v[130:131], v[170:171], 0, v[180:181]
	v_lshlrev_b64 v[176:177], 11, v[174:175]
	global_load_dwordx4 v[142:145], v[130:131], off
	global_load_dwordx4 v[138:141], v[130:131], off offset:256
	v_lshl_add_u64 v[130:131], v[170:171], 0, v[176:177]
	v_cmp_eq_u32_e32 vcc, 0, v132
	global_load_dwordx4 v[134:137], v[130:131], off
	s_nop 0
	global_load_dwordx4 v[130:133], v[130:131], off offset:256
	v_lshl_add_u64 v[204:205], s[36:37], 0, v[204:205]
	v_lshl_add_u64 v[202:203], v[204:205], 0, v[202:203]
	s_waitcnt vmcnt(7)
	v_lshlrev_b32_e32 v206, 16, v192
	v_and_b32_e32 v207, 0xffff0000, v192
	v_lshlrev_b32_e32 v192, 16, v193
	v_and_b32_e32 v193, 0xffff0000, v193
	v_lshlrev_b32_e32 v208, 16, v194
	v_and_b32_e32 v209, 0xffff0000, v194
	v_lshlrev_b32_e32 v194, 16, v195
	v_and_b32_e32 v195, 0xffff0000, v195
	v_pk_add_f32 v[128:129], v[128:129], v[192:193]
	v_pk_add_f32 v[126:127], v[126:127], v[206:207]
	v_pk_add_f32 v[192:193], v[124:125], v[194:195]
	v_pk_add_f32 v[194:195], v[122:123], v[208:209]
	v_cvt_pk_bf16_f32 v122, v126, v127
	v_cvt_pk_bf16_f32 v123, v128, v129
	v_cvt_pk_bf16_f32 v124, v194, v195
	v_cvt_pk_bf16_f32 v125, v192, v193
	global_store_dwordx4 v[202:203], v[122:125], off
	s_nop 1
	v_mul_f32_e32 v122, v127, v127
	v_mul_f32_e32 v123, v129, v129
	v_fmac_f32_e32 v122, v126, v126
	v_fmac_f32_e32 v123, v128, v128
	v_add_f32_e32 v122, v122, v123
	v_mul_f32_e32 v123, v195, v195
	v_mul_f32_e32 v124, v193, v193
	v_fmac_f32_e32 v123, v194, v194
	v_fmac_f32_e32 v124, v192, v192
	v_add_f32_e32 v123, v123, v124
	v_add_f32_e32 v192, v122, v123
	s_waitcnt vmcnt(7)
	v_lshlrev_b32_e32 v122, 16, v154
	v_and_b32_e32 v123, 0xffff0000, v154
	v_lshlrev_b32_e32 v124, 16, v155
	v_and_b32_e32 v125, 0xffff0000, v155
	v_lshlrev_b32_e32 v126, 16, v156
	v_and_b32_e32 v127, 0xffff0000, v156
	v_lshlrev_b32_e32 v128, 16, v157
	v_and_b32_e32 v129, 0xffff0000, v157
	v_pk_add_f32 v[120:121], v[120:121], v[124:125]
	v_pk_add_f32 v[118:119], v[118:119], v[122:123]
	v_pk_add_f32 v[122:123], v[116:117], v[128:129]
	v_pk_add_f32 v[124:125], v[114:115], v[126:127]
	v_cvt_pk_bf16_f32 v114, v118, v119
	v_cvt_pk_bf16_f32 v115, v120, v121
	v_cvt_pk_bf16_f32 v116, v124, v125
	v_cvt_pk_bf16_f32 v117, v122, v123
	global_store_dwordx4 v[202:203], v[114:117], off offset:256
	s_nop 1
	v_mul_f32_e32 v114, v119, v119
	v_mul_f32_e32 v115, v121, v121
	v_fmac_f32_e32 v114, v118, v118
	v_fmac_f32_e32 v115, v120, v120
	v_add_f32_e32 v114, v114, v115
	v_mul_f32_e32 v115, v125, v125
	v_mul_f32_e32 v116, v123, v123
	v_fmac_f32_e32 v115, v124, v124
	v_fmac_f32_e32 v116, v122, v122
	v_add_f32_e32 v115, v115, v116
	v_add_f32_e32 v114, v114, v115
	v_add_f32_e32 v114, v192, v114
	ds_bpermute_b32 v115, v191, v114
	s_waitcnt lgkmcnt(0)
	v_add_f32_e32 v114, v114, v115
	ds_bpermute_b32 v115, v190, v114
	s_and_saveexec_b64 s[60:61], vcc
	s_cbranch_execz .LBB0_69
	s_waitcnt lgkmcnt(0)
	v_add_f32_e32 v116, v114, v115
	s_lshl_b32 s22, s46, 2
	v_lshlrev_b64 v[114:115], 6, v[172:173]
	s_ashr_i32 s23, s22, 31
	v_lshl_add_u64 v[114:115], s[84:85], 0, v[114:115]
	v_lshl_add_u64 v[114:115], s[22:23], 2, v[114:115]
	s_lshl_b32 s86, s74, 2
	v_lshl_add_u64 v[114:115], v[114:115], 0, s[86:87]
	global_store_dword v[114:115], v116, off
.LBB0_69:
	s_or_b64 exec, exec, s[60:61]
	s_waitcnt vmcnt(7)
	v_lshlrev_b32_e32 v114, 16, v150
	s_waitcnt lgkmcnt(0)
	v_and_b32_e32 v115, 0xffff0000, v150
	v_lshlrev_b32_e32 v116, 16, v151
	v_and_b32_e32 v117, 0xffff0000, v151
	v_lshlrev_b32_e32 v118, 16, v152
	v_and_b32_e32 v119, 0xffff0000, v152
	v_pk_add_f32 v[110:111], v[110:111], v[114:115]
	v_pk_add_f32 v[112:113], v[112:113], v[116:117]
	v_pk_add_f32 v[116:117], v[106:107], v[118:119]
	v_cvt_pk_bf16_f32 v106, v110, v111
	v_mul_f32_e32 v111, v111, v111
	v_lshlrev_b32_e32 v120, 16, v153
	v_and_b32_e32 v121, 0xffff0000, v153
	v_fmac_f32_e32 v111, v110, v110
	v_mul_f32_e32 v110, v113, v113
	v_pk_add_f32 v[114:115], v[108:109], v[120:121]
	v_fmac_f32_e32 v110, v112, v112
	v_cvt_pk_bf16_f32 v107, v112, v113
	v_add_f32_e32 v110, v111, v110
	v_mul_f32_e32 v111, v117, v117
	v_mul_f32_e32 v112, v115, v115
	v_fmac_f32_e32 v111, v116, v116
	v_fmac_f32_e32 v112, v114, v114
	v_add_f32_e32 v111, v111, v112
	v_add_f32_e32 v118, v110, v111
	s_waitcnt vmcnt(6)
	v_lshlrev_b32_e32 v110, 16, v146
	v_and_b32_e32 v111, 0xffff0000, v146
	v_lshlrev_b32_e32 v112, 16, v147
	v_and_b32_e32 v113, 0xffff0000, v147
	v_cvt_pk_bf16_f32 v109, v114, v115
	v_lshlrev_b32_e32 v114, 16, v148
	v_and_b32_e32 v115, 0xffff0000, v148
	v_pk_add_f32 v[104:105], v[104:105], v[112:113]
	v_pk_add_f32 v[102:103], v[102:103], v[110:111]
	v_cvt_pk_bf16_f32 v108, v116, v117
	v_lshlrev_b32_e32 v116, 16, v149
	v_and_b32_e32 v117, 0xffff0000, v149
	v_pk_add_f32 v[112:113], v[98:99], v[114:115]
	v_mul_f32_e32 v98, v103, v103
	v_mul_f32_e32 v99, v105, v105
	v_pk_add_f32 v[110:111], v[100:101], v[116:117]
	v_fmac_f32_e32 v98, v102, v102
	v_fmac_f32_e32 v99, v104, v104
	v_add_f32_e32 v98, v98, v99
	v_mul_f32_e32 v99, v113, v113
	v_mul_f32_e32 v100, v111, v111
	v_fmac_f32_e32 v99, v112, v112
	v_fmac_f32_e32 v100, v110, v110
	v_add_f32_e32 v99, v99, v100
	v_add_f32_e32 v98, v98, v99
	v_add_f32_e32 v101, v118, v98
	ds_bpermute_b32 v116, v191, v101
	v_lshl_add_u64 v[98:99], s[36:37], 0, v[184:185]
	v_lshl_add_u64 v[114:115], v[168:169], 1, v[98:99]
	v_cvt_pk_bf16_f32 v100, v102, v103
	v_cvt_pk_bf16_f32 v102, v112, v113
	s_waitcnt lgkmcnt(0)
	v_add_f32_e32 v98, v101, v116
	ds_bpermute_b32 v99, v190, v98
	v_cvt_pk_bf16_f32 v101, v104, v105
	v_cvt_pk_bf16_f32 v103, v110, v111
	global_store_dwordx4 v[114:115], v[106:109], off
	global_store_dwordx4 v[114:115], v[100:103], off offset:256
	s_and_saveexec_b64 s[60:61], vcc
	s_cbranch_execz .LBB0_71
	s_waitcnt lgkmcnt(0)
	v_add_f32_e32 v100, v98, v99
	s_lshl_b32 s22, s46, 2
	v_lshlrev_b64 v[98:99], 6, v[182:183]
	s_ashr_i32 s23, s22, 31
	v_lshl_add_u64 v[98:99], s[84:85], 0, v[98:99]
	v_lshl_add_u64 v[98:99], s[22:23], 2, v[98:99]
	s_lshl_b32 s86, s74, 2
	v_lshl_add_u64 v[98:99], v[98:99], 0, s[86:87]
	global_store_dword v[98:99], v100, off
; __device__ __forceinline__ float shx(float v, int lane, int o) { return __int_as_float(__builtin_amdgcn_ds_bpermute((lane ^ o) << 2, __float_as_int(v))); }
; __device__ __forceinline__ u32x4 pack8(const f32x4 a, const f32x4 b) { u32x4 w; w.x = cvt_pk_bf16(a[0], a[1]); w.y = cvt_pk_bf16(a[2], a[3]); w.z = cvt_pk_bf16(b[0], b[1]); w.w = cvt_pk_bf16(b[2], b[3]); return w; }
; __device__ __forceinline__ void unpack8(const u32x4 w, f32x4& a, f32x4& b) { a = (f32x4){bflo(w.x), bfhi(w.x), bflo(w.y), bfhi(w.y)}; b = (f32x4){bflo(w.z), bfhi(w.z), bflo(w.w), bfhi(w.w)}; }
;     __device__ __forceinline__ void operator()(const Acc& acc, const Unit& u, int wr, int wc, int fr, int fq) const {
;     ...
;             for (int m = 0; m < 4; ++m) { const size_t row = (size_t)(row0 + ai * 128 + m * 16); float sq = 0.f;
; #pragma unroll
;                 for (int bj = 0; bj < 2; ++bj) { f32x4 o0, o1; unpack8(hv[m][bj], o0, o1); o0 += acc[ai][bj][m][0] * sc; o1 += acc[ai][bj][m][1] * sc;
;                     *(u32x4*)(hb + row * DM + col0 + bj * 128) = pack8(o0, o1);
;                     sq += ((o0[0] * o0[0] + o0[1] * o0[1]) + (o0[2] * o0[2] + o0[3] * o0[3])) + ((o1[0] * o1[0] + o1[1] * o1[1]) + (o1[2] * o1[2] + o1[3] * o1[3])); }
;                 const int lane = fq * 16 + fr; sq += shx(sq, lane, 16); sq += shx(sq, lane, 32);
;                 if (fq == 0) ssq[row * 16 + u.pn * 4 + wc] = sq; } }
.LBB0_71:
	s_or_b64 exec, exec, s[60:61]
	s_waitcnt vmcnt(7)
	v_lshlrev_b32_e32 v98, 16, v142
	s_waitcnt lgkmcnt(0)
	v_and_b32_e32 v99, 0xffff0000, v142
	v_lshlrev_b32_e32 v100, 16, v143
	v_and_b32_e32 v101, 0xffff0000, v143
	v_lshlrev_b32_e32 v102, 16, v144
	v_and_b32_e32 v103, 0xffff0000, v144
	v_pk_add_f32 v[94:95], v[94:95], v[98:99]
	v_pk_add_f32 v[96:97], v[96:97], v[100:101]
	v_pk_add_f32 v[100:101], v[90:91], v[102:103]
	v_cvt_pk_bf16_f32 v90, v94, v95
	v_mul_f32_e32 v95, v95, v95
	v_lshlrev_b32_e32 v104, 16, v145
	v_and_b32_e32 v105, 0xffff0000, v145
	v_fmac_f32_e32 v95, v94, v94
	v_mul_f32_e32 v94, v97, v97
	v_pk_add_f32 v[98:99], v[92:93], v[104:105]
	v_fmac_f32_e32 v94, v96, v96
	v_cvt_pk_bf16_f32 v91, v96, v97
	v_add_f32_e32 v94, v95, v94
	v_mul_f32_e32 v95, v101, v101
	v_mul_f32_e32 v96, v99, v99
	v_fmac_f32_e32 v95, v100, v100
	v_fmac_f32_e32 v96, v98, v98
	v_add_f32_e32 v95, v95, v96
	v_add_f32_e32 v102, v94, v95
	s_waitcnt vmcnt(6)
	v_lshlrev_b32_e32 v94, 16, v138
	v_and_b32_e32 v95, 0xffff0000, v138
	v_lshlrev_b32_e32 v96, 16, v139
	v_and_b32_e32 v97, 0xffff0000, v139
	v_cvt_pk_bf16_f32 v93, v98, v99
	v_lshlrev_b32_e32 v98, 16, v140
	v_and_b32_e32 v99, 0xffff0000, v140
	v_pk_add_f32 v[88:89], v[88:89], v[96:97]
	v_pk_add_f32 v[86:87], v[86:87], v[94:95]
	v_cvt_pk_bf16_f32 v92, v100, v101
	v_lshlrev_b32_e32 v100, 16, v141
	v_and_b32_e32 v101, 0xffff0000, v141
	v_pk_add_f32 v[96:97], v[82:83], v[98:99]
	v_mul_f32_e32 v82, v87, v87
	v_mul_f32_e32 v83, v89, v89
	v_pk_add_f32 v[94:95], v[84:85], v[100:101]
	v_fmac_f32_e32 v82, v86, v86
	v_fmac_f32_e32 v83, v88, v88
	v_add_f32_e32 v82, v82, v83
	v_mul_f32_e32 v83, v97, v97
	v_mul_f32_e32 v84, v95, v95
	v_fmac_f32_e32 v83, v96, v96
	v_fmac_f32_e32 v84, v94, v94
	v_add_f32_e32 v83, v83, v84
	v_add_f32_e32 v82, v82, v83
	v_add_f32_e32 v85, v102, v82
	ds_bpermute_b32 v100, v191, v85
	v_lshl_add_u64 v[82:83], s[36:37], 0, v[180:181]
	v_lshl_add_u64 v[98:99], v[168:169], 1, v[82:83]
	v_cvt_pk_bf16_f32 v84, v86, v87
	v_cvt_pk_bf16_f32 v86, v96, v97
	s_waitcnt lgkmcnt(0)
	v_add_f32_e32 v82, v85, v100
	ds_bpermute_b32 v83, v190, v82
	v_cvt_pk_bf16_f32 v85, v88, v89
	v_cvt_pk_bf16_f32 v87, v94, v95
	global_store_dwordx4 v[98:99], v[90:93], off
	global_store_dwordx4 v[98:99], v[84:87], off offset:256
	s_and_saveexec_b64 s[60:61], vcc
	s_cbranch_execz .LBB0_73
	s_waitcnt lgkmcnt(0)
	v_add_f32_e32 v84, v82, v83
	s_lshl_b32 s22, s46, 2
	v_lshlrev_b64 v[82:83], 6, v[178:179]
	s_ashr_i32 s23, s22, 31
	v_lshl_add_u64 v[82:83], s[84:85], 0, v[82:83]
	v_lshl_add_u64 v[82:83], s[22:23], 2, v[82:83]
	s_lshl_b32 s86, s74, 2
	v_lshl_add_u64 v[82:83], v[82:83], 0, s[86:87]
	global_store_dword v[82:83], v84, off
.LBB0_73:
	s_or_b64 exec, exec, s[60:61]
	s_waitcnt vmcnt(7)
	v_lshlrev_b32_e32 v82, 16, v134
	s_waitcnt lgkmcnt(0)
	v_and_b32_e32 v83, 0xffff0000, v134
	v_lshlrev_b32_e32 v84, 16, v135
	v_and_b32_e32 v85, 0xffff0000, v135
	v_lshlrev_b32_e32 v86, 16, v136
	v_and_b32_e32 v87, 0xffff0000, v136
	v_pk_add_f32 v[78:79], v[78:79], v[82:83]
	v_pk_add_f32 v[80:81], v[80:81], v[84:85]
	v_pk_add_f32 v[84:85], v[74:75], v[86:87]
	v_cvt_pk_bf16_f32 v74, v78, v79
	v_mul_f32_e32 v79, v79, v79
	v_lshlrev_b32_e32 v88, 16, v137
	v_and_b32_e32 v89, 0xffff0000, v137
	v_fmac_f32_e32 v79, v78, v78
	v_mul_f32_e32 v78, v81, v81
	v_pk_add_f32 v[82:83], v[76:77], v[88:89]
	v_fmac_f32_e32 v78, v80, v80
	v_cvt_pk_bf16_f32 v75, v80, v81
	v_add_f32_e32 v78, v79, v78
	v_mul_f32_e32 v79, v85, v85
	v_mul_f32_e32 v80, v83, v83
	v_fmac_f32_e32 v79, v84, v84
	v_fmac_f32_e32 v80, v82, v82
	v_add_f32_e32 v79, v79, v80
	v_add_f32_e32 v86, v78, v79
	s_waitcnt vmcnt(6)
	v_lshlrev_b32_e32 v78, 16, v130
	v_and_b32_e32 v79, 0xffff0000, v130
	v_lshlrev_b32_e32 v80, 16, v131
	v_and_b32_e32 v81, 0xffff0000, v131
	v_cvt_pk_bf16_f32 v77, v82, v83
	v_lshlrev_b32_e32 v82, 16, v132
	v_and_b32_e32 v83, 0xffff0000, v132
	v_pk_add_f32 v[72:73], v[72:73], v[80:81]
	v_pk_add_f32 v[70:71], v[70:71], v[78:79]
	v_cvt_pk_bf16_f32 v76, v84, v85
	v_lshlrev_b32_e32 v84, 16, v133
	v_and_b32_e32 v85, 0xffff0000, v133
	v_pk_add_f32 v[80:81], v[66:67], v[82:83]
	v_mul_f32_e32 v66, v71, v71
	v_mul_f32_e32 v67, v73, v73
	v_pk_add_f32 v[78:79], v[68:69], v[84:85]
	v_fmac_f32_e32 v66, v70, v70
	v_fmac_f32_e32 v67, v72, v72
	v_add_f32_e32 v66, v66, v67
	v_mul_f32_e32 v67, v81, v81
	v_mul_f32_e32 v68, v79, v79
	v_fmac_f32_e32 v67, v80, v80
	v_fmac_f32_e32 v68, v78, v78
	v_add_f32_e32 v67, v67, v68
	v_add_f32_e32 v66, v66, v67
	v_add_f32_e32 v69, v86, v66
	ds_bpermute_b32 v84, v191, v69
	v_lshl_add_u64 v[66:67], s[36:37], 0, v[176:177]
	v_lshl_add_u64 v[82:83], v[168:169], 1, v[66:67]
	v_cvt_pk_bf16_f32 v68, v70, v71
	v_cvt_pk_bf16_f32 v70, v80, v81
	s_waitcnt lgkmcnt(0)
	v_add_f32_e32 v66, v69, v84
	ds_bpermute_b32 v67, v190, v66
	v_cvt_pk_bf16_f32 v69, v72, v73
	v_cvt_pk_bf16_f32 v71, v78, v79
	global_store_dwordx4 v[82:83], v[74:77], off
	global_store_dwordx4 v[82:83], v[68:71], off offset:256
	s_and_saveexec_b64 s[60:61], vcc
	s_cbranch_execz .LBB0_75
	s_waitcnt lgkmcnt(0)
	v_add_f32_e32 v68, v66, v67
	s_lshl_b32 s22, s46, 2
	v_lshlrev_b64 v[66:67], 6, v[174:175]
	s_ashr_i32 s23, s22, 31
	v_lshl_add_u64 v[66:67], s[84:85], 0, v[66:67]
	v_lshl_add_u64 v[66:67], s[22:23], 2, v[66:67]
	s_lshl_b32 s86, s74, 2
	v_lshl_add_u64 v[66:67], v[66:67], 0, s[86:87]
	global_store_dword v[66:67], v68, off

; __device__ __forceinline__ float shx(float v, int lane, int o) { return __int_as_float(__builtin_amdgcn_ds_bpermute((lane ^ o) << 2, __float_as_int(v))); }
; __device__ __forceinline__ u32x4 pack8(const f32x4 a, const f32x4 b) { u32x4 w; w.x = cvt_pk_bf16(a[0], a[1]); w.y = cvt_pk_bf16(a[2], a[3]); w.z = cvt_pk_bf16(b[0], b[1]); w.w = cvt_pk_bf16(b[2], b[3]); return w; }
; __device__ __forceinline__ void unpack8(const u32x4 w, f32x4& a, f32x4& b) { a = (f32x4){bflo(w.x), bfhi(w.x), bflo(w.y), bfhi(w.y)}; b = (f32x4){bflo(w.z), bfhi(w.z), bflo(w.w), bfhi(w.w)}; }
;     __device__ __forceinline__ void operator()(const Acc& acc, const Unit& u, int wr, int wc, int fr, int fq) const {
;     ...
;         if (u.split) {
;             float* pt = part + (size_t)(u.split - 1) * 256 * DM;
; #pragma unroll
;             for (int ai = 0; ai < 2; ++ai)
; #pragma unroll
;                 for (int m = 0; m < 4; ++m)
; #pragma unroll
;                     for (int bj = 0; bj < 2; ++bj)
; #pragma unroll
;                         for (int n = 0; n < 2; ++n) *(f32x4*)(pt + (size_t)(wr * 64 + fr + ai * 128 + m * 16) * DM + col0 + bj * 128 + n * 4) = acc[ai][bj][m][n] * sc;
;             return; }
; #pragma unroll
;         for (int ai = 0; ai < 2; ++ai) {
;             u32x4 hv[4][2];
; #pragma unroll
;             for (int m = 0; m < 4; ++m)
; #pragma unroll
;                 for (int bj = 0; bj < 2; ++bj) hv[m][bj] = *(const u32x4*)(hb + (size_t)(row0 + ai * 128 + m * 16) * DM + col0 + bj * 128);
; #pragma unroll
;             for (int m = 0; m < 4; ++m) { const size_t row = (size_t)(row0 + ai * 128 + m * 16); float sq = 0.f;
; #pragma unroll
;                 for (int bj = 0; bj < 2; ++bj) { f32x4 o0, o1; unpack8(hv[m][bj], o0, o1); o0 += acc[ai][bj][m][0] * sc; o1 += acc[ai][bj][m][1] * sc;
;                     *(u32x4*)(hb + row * DM + col0 + bj * 128) = pack8(o0, o1);
;                     sq += ((o0[0] * o0[0] + o0[1] * o0[1]) + (o0[2] * o0[2] + o0[3] * o0[3])) + ((o1[0] * o1[0] + o1[1] * o1[1]) + (o1[2] * o1[2] + o1[3] * o1[3])); }
;                 const int lane = fq * 16 + fr; sq += shx(sq, lane, 16); sq += shx(sq, lane, 32);
;                 if (fq == 0) ssq[row * 16 + u.pn * 4 + wc] = sq; } }
.LBB0_213:
	v_readlane_b32 s92, v253, 42
	s_andn2_b64 vcc, exec, s[66:67]
	s_cbranch_vccnz .LBB0_197
	v_lshl_add_u32 v172, s64, 8, v130
	v_lshlrev_b32_e32 v130, 2, v133
	v_lshlrev_b64 v[202:203], 1, v[168:169]
	v_ashrrev_i32_e32 v173, 31, v172
	v_lshl_add_u32 v130, v132, 6, v130
	v_lshl_add_u64 v[170:171], s[36:37], 0, v[202:203]
	v_lshlrev_b64 v[204:205], 11, v[172:173]
	v_xor_b32_e32 v191, 64, v130
	v_xor_b32_e32 v190, 0x80, v130
	v_lshl_add_u64 v[130:131], v[170:171], 0, v[204:205]
	global_load_dwordx4 v[192:195], v[130:131], off
	global_load_dwordx4 v[154:157], v[130:131], off offset:256
	v_add_u32_e32 v182, 16, v172
	v_ashrrev_i32_e32 v183, 31, v182
	v_add_u32_e32 v178, 32, v172
	v_lshlrev_b64 v[184:185], 11, v[182:183]
	v_ashrrev_i32_e32 v179, 31, v178
	v_add_u32_e32 v174, 48, v172
	v_lshl_add_u64 v[130:131], v[170:171], 0, v[184:185]
	v_lshlrev_b64 v[180:181], 11, v[178:179]
	v_ashrrev_i32_e32 v175, 31, v174
	global_load_dwordx4 v[150:153], v[130:131], off
	global_load_dwordx4 v[146:149], v[130:131], off offset:256
	v_lshl_add_u64 v[130:131], v[170:171], 0, v[180:181]
	v_lshlrev_b64 v[176:177], 11, v[174:175]
	global_load_dwordx4 v[142:145], v[130:131], off
	global_load_dwordx4 v[138:141], v[130:131], off offset:256
	v_lshl_add_u64 v[130:131], v[170:171], 0, v[176:177]
	v_cmp_eq_u32_e32 vcc, 0, v132
	global_load_dwordx4 v[134:137], v[130:131], off
	s_nop 0
	global_load_dwordx4 v[130:133], v[130:131], off offset:256
	v_lshl_add_u64 v[204:205], s[36:37], 0, v[204:205]
	v_lshl_add_u64 v[202:203], v[204:205], 0, v[202:203]
	s_waitcnt vmcnt(7)
	v_lshlrev_b32_e32 v206, 16, v192
	v_and_b32_e32 v207, 0xffff0000, v192
	v_lshlrev_b32_e32 v192, 16, v193
	v_and_b32_e32 v193, 0xffff0000, v193
	v_lshlrev_b32_e32 v208, 16, v194
	v_and_b32_e32 v209, 0xffff0000, v194
	v_lshlrev_b32_e32 v194, 16, v195
	v_and_b32_e32 v195, 0xffff0000, v195
	v_pk_add_f32 v[128:129], v[128:129], v[192:193]
	v_pk_add_f32 v[126:127], v[126:127], v[206:207]
	v_pk_add_f32 v[192:193], v[124:125], v[194:195]
	v_pk_add_f32 v[194:195], v[122:123], v[208:209]
	v_cvt_pk_bf16_f32 v122, v126, v127
	v_cvt_pk_bf16_f32 v123, v128, v129
	v_cvt_pk_bf16_f32 v124, v194, v195
	v_cvt_pk_bf16_f32 v125, v192, v193
	global_store_dwordx4 v[202:203], v[122:125], off
	s_nop 1
	v_mul_f32_e32 v122, v127, v127
	v_mul_f32_e32 v123, v129, v129
	v_fmac_f32_e32 v122, v126, v126
	v_fmac_f32_e32 v123, v128, v128
	v_add_f32_e32 v122, v122, v123
	v_mul_f32_e32 v123, v195, v195
	v_mul_f32_e32 v124, v193, v193
	v_fmac_f32_e32 v123, v194, v194
	v_fmac_f32_e32 v124, v192, v192
	v_add_f32_e32 v123, v123, v124
	v_add_f32_e32 v192, v122, v123
	s_waitcnt vmcnt(7)
	v_lshlrev_b32_e32 v122, 16, v154
	v_and_b32_e32 v123, 0xffff0000, v154
	v_lshlrev_b32_e32 v124, 16, v155
	v_and_b32_e32 v125, 0xffff0000, v155
	v_lshlrev_b32_e32 v126, 16, v156
	v_and_b32_e32 v127, 0xffff0000, v156
	v_lshlrev_b32_e32 v128, 16, v157
	v_and_b32_e32 v129, 0xffff0000, v157
	v_pk_add_f32 v[120:121], v[120:121], v[124:125]
	v_pk_add_f32 v[118:119], v[118:119], v[122:123]
	v_pk_add_f32 v[122:123], v[116:117], v[128:129]
	v_pk_add_f32 v[124:125], v[114:115], v[126:127]
	v_cvt_pk_bf16_f32 v114, v118, v119
	v_cvt_pk_bf16_f32 v115, v120, v121
	v_cvt_pk_bf16_f32 v116, v124, v125
	v_cvt_pk_bf16_f32 v117, v122, v123
	global_store_dwordx4 v[202:203], v[114:117], off offset:256
	s_nop 1
	v_mul_f32_e32 v114, v119, v119
	v_mul_f32_e32 v115, v121, v121
	v_fmac_f32_e32 v114, v118, v118
	v_fmac_f32_e32 v115, v120, v120
	v_add_f32_e32 v114, v114, v115
	v_mul_f32_e32 v115, v125, v125
	v_mul_f32_e32 v116, v123, v123
	v_fmac_f32_e32 v115, v124, v124
	v_fmac_f32_e32 v116, v122, v122
	v_add_f32_e32 v115, v115, v116
	v_add_f32_e32 v114, v114, v115
	v_add_f32_e32 v114, v192, v114
	ds_bpermute_b32 v115, v191, v114
	s_waitcnt lgkmcnt(0)
	v_add_f32_e32 v114, v114, v115
	ds_bpermute_b32 v115, v190, v114
	s_and_saveexec_b64 s[64:65], vcc
	s_cbranch_execz .LBB0_216
	s_waitcnt lgkmcnt(0)
	v_add_f32_e32 v116, v114, v115
	s_lshl_b32 s66, s42, 2
	v_lshlrev_b64 v[114:115], 6, v[172:173]
	s_ashr_i32 s67, s66, 31
	v_lshl_add_u64 v[114:115], s[4:5], 0, v[114:115]
	v_lshl_add_u64 v[114:115], s[66:67], 2, v[114:115]
	s_lshl_b32 s86, s29, 2
	v_lshl_add_u64 v[114:115], v[114:115], 0, s[86:87]
	global_store_dword v[114:115], v116, off
; __device__ __forceinline__ float shx(float v, int lane, int o) { return __int_as_float(__builtin_amdgcn_ds_bpermute((lane ^ o) << 2, __float_as_int(v))); }
; __device__ __forceinline__ u32x4 pack8(const f32x4 a, const f32x4 b) { u32x4 w; w.x = cvt_pk_bf16(a[0], a[1]); w.y = cvt_pk_bf16(a[2], a[3]); w.z = cvt_pk_bf16(b[0], b[1]); w.w = cvt_pk_bf16(b[2], b[3]); return w; }
; __device__ __forceinline__ void unpack8(const u32x4 w, f32x4& a, f32x4& b) { a = (f32x4){bflo(w.x), bfhi(w.x), bflo(w.y), bfhi(w.y)}; b = (f32x4){bflo(w.z), bfhi(w.z), bflo(w.w), bfhi(w.w)}; }
;     __device__ __forceinline__ void operator()(const Acc& acc, const Unit& u, int wr, int wc, int fr, int fq) const {
;     ...
;             for (int m = 0; m < 4; ++m) { const size_t row = (size_t)(row0 + ai * 128 + m * 16); float sq = 0.f;
; #pragma unroll
;                 for (int bj = 0; bj < 2; ++bj) { f32x4 o0, o1; unpack8(hv[m][bj], o0, o1); o0 += acc[ai][bj][m][0] * sc; o1 += acc[ai][bj][m][1] * sc;
;                     *(u32x4*)(hb + row * DM + col0 + bj * 128) = pack8(o0, o1);
;                     sq += ((o0[0] * o0[0] + o0[1] * o0[1]) + (o0[2] * o0[2] + o0[3] * o0[3])) + ((o1[0] * o1[0] + o1[1] * o1[1]) + (o1[2] * o1[2] + o1[3] * o1[3])); }
;                 const int lane = fq * 16 + fr; sq += shx(sq, lane, 16); sq += shx(sq, lane, 32);
;                 if (fq == 0) ssq[row * 16 + u.pn * 4 + wc] = sq; } }
.LBB0_216:
	s_or_b64 exec, exec, s[64:65]
	s_waitcnt vmcnt(7)
	v_lshlrev_b32_e32 v114, 16, v150
	s_waitcnt lgkmcnt(0)
	v_and_b32_e32 v115, 0xffff0000, v150
	v_lshlrev_b32_e32 v116, 16, v151
	v_and_b32_e32 v117, 0xffff0000, v151
	v_lshlrev_b32_e32 v118, 16, v152
	v_and_b32_e32 v119, 0xffff0000, v152
	v_pk_add_f32 v[110:111], v[110:111], v[114:115]
	v_pk_add_f32 v[112:113], v[112:113], v[116:117]
	v_pk_add_f32 v[116:117], v[106:107], v[118:119]
	v_cvt_pk_bf16_f32 v106, v110, v111
	v_mul_f32_e32 v111, v111, v111
	v_lshlrev_b32_e32 v120, 16, v153
	v_and_b32_e32 v121, 0xffff0000, v153
	v_fmac_f32_e32 v111, v110, v110
	v_mul_f32_e32 v110, v113, v113
	v_pk_add_f32 v[114:115], v[108:109], v[120:121]
	v_fmac_f32_e32 v110, v112, v112
	v_cvt_pk_bf16_f32 v107, v112, v113
	v_add_f32_e32 v110, v111, v110
	v_mul_f32_e32 v111, v117, v117
	v_mul_f32_e32 v112, v115, v115
	v_fmac_f32_e32 v111, v116, v116
	v_fmac_f32_e32 v112, v114, v114
	v_add_f32_e32 v111, v111, v112
	v_add_f32_e32 v118, v110, v111
	s_waitcnt vmcnt(6)
	v_lshlrev_b32_e32 v110, 16, v146
	v_and_b32_e32 v111, 0xffff0000, v146
	v_lshlrev_b32_e32 v112, 16, v147
	v_and_b32_e32 v113, 0xffff0000, v147
	v_cvt_pk_bf16_f32 v109, v114, v115
	v_lshlrev_b32_e32 v114, 16, v148
	v_and_b32_e32 v115, 0xffff0000, v148
	v_pk_add_f32 v[104:105], v[104:105], v[112:113]
	v_pk_add_f32 v[102:103], v[102:103], v[110:111]
	v_cvt_pk_bf16_f32 v108, v116, v117
	v_lshlrev_b32_e32 v116, 16, v149
	v_and_b32_e32 v117, 0xffff0000, v149
	v_pk_add_f32 v[112:113], v[98:99], v[114:115]
	v_mul_f32_e32 v98, v103, v103
	v_mul_f32_e32 v99, v105, v105
	v_pk_add_f32 v[110:111], v[100:101], v[116:117]
	v_fmac_f32_e32 v98, v102, v102
	v_fmac_f32_e32 v99, v104, v104
	v_add_f32_e32 v98, v98, v99
	v_mul_f32_e32 v99, v113, v113
	v_mul_f32_e32 v100, v111, v111
	v_fmac_f32_e32 v99, v112, v112
	v_fmac_f32_e32 v100, v110, v110
	v_add_f32_e32 v99, v99, v100
	v_add_f32_e32 v98, v98, v99
	v_add_f32_e32 v101, v118, v98
	ds_bpermute_b32 v116, v191, v101
	v_lshl_add_u64 v[98:99], s[36:37], 0, v[184:185]
	v_lshl_add_u64 v[114:115], v[168:169], 1, v[98:99]
	v_cvt_pk_bf16_f32 v100, v102, v103
	v_cvt_pk_bf16_f32 v102, v112, v113
	s_waitcnt lgkmcnt(0)
	v_add_f32_e32 v98, v101, v116
	ds_bpermute_b32 v99, v190, v98
	v_cvt_pk_bf16_f32 v101, v104, v105
	v_cvt_pk_bf16_f32 v103, v110, v111
	global_store_dwordx4 v[114:115], v[106:109], off
	global_store_dwordx4 v[114:115], v[100:103], off offset:256
	s_and_saveexec_b64 s[64:65], vcc
	s_cbranch_execz .LBB0_218
	s_waitcnt lgkmcnt(0)
	v_add_f32_e32 v100, v98, v99
	s_lshl_b32 s66, s42, 2
	v_lshlrev_b64 v[98:99], 6, v[182:183]
	s_ashr_i32 s67, s66, 31
	v_lshl_add_u64 v[98:99], s[4:5], 0, v[98:99]
	v_lshl_add_u64 v[98:99], s[66:67], 2, v[98:99]
	s_lshl_b32 s86, s29, 2
	v_lshl_add_u64 v[98:99], v[98:99], 0, s[86:87]
	global_store_dword v[98:99], v100, off
; __device__ __forceinline__ float shx(float v, int lane, int o) { return __int_as_float(__builtin_amdgcn_ds_bpermute((lane ^ o) << 2, __float_as_int(v))); }
; __device__ __forceinline__ u32x4 pack8(const f32x4 a, const f32x4 b) { u32x4 w; w.x = cvt_pk_bf16(a[0], a[1]); w.y = cvt_pk_bf16(a[2], a[3]); w.z = cvt_pk_bf16(b[0], b[1]); w.w = cvt_pk_bf16(b[2], b[3]); return w; }
; __device__ __forceinline__ void unpack8(const u32x4 w, f32x4& a, f32x4& b) { a = (f32x4){bflo(w.x), bfhi(w.x), bflo(w.y), bfhi(w.y)}; b = (f32x4){bflo(w.z), bfhi(w.z), bflo(w.w), bfhi(w.w)}; }
;     __device__ __forceinline__ void operator()(const Acc& acc, const Unit& u, int wr, int wc, int fr, int fq) const {
;     ...
;             for (int m = 0; m < 4; ++m) { const size_t row = (size_t)(row0 + ai * 128 + m * 16); float sq = 0.f;
; #pragma unroll
;                 for (int bj = 0; bj < 2; ++bj) { f32x4 o0, o1; unpack8(hv[m][bj], o0, o1); o0 += acc[ai][bj][m][0] * sc; o1 += acc[ai][bj][m][1] * sc;
;                     *(u32x4*)(hb + row * DM + col0 + bj * 128) = pack8(o0, o1);
;                     sq += ((o0[0] * o0[0] + o0[1] * o0[1]) + (o0[2] * o0[2] + o0[3] * o0[3])) + ((o1[0] * o1[0] + o1[1] * o1[1]) + (o1[2] * o1[2] + o1[3] * o1[3])); }
;                 const int lane = fq * 16 + fr; sq += shx(sq, lane, 16); sq += shx(sq, lane, 32);
;                 if (fq == 0) ssq[row * 16 + u.pn * 4 + wc] = sq; } }
.LBB0_218:
	s_or_b64 exec, exec, s[64:65]
	s_waitcnt vmcnt(7)
	v_lshlrev_b32_e32 v98, 16, v142
	s_waitcnt lgkmcnt(0)
	v_and_b32_e32 v99, 0xffff0000, v142
	v_lshlrev_b32_e32 v100, 16, v143
	v_and_b32_e32 v101, 0xffff0000, v143
	v_lshlrev_b32_e32 v102, 16, v144
	v_and_b32_e32 v103, 0xffff0000, v144
	v_pk_add_f32 v[94:95], v[94:95], v[98:99]
	v_pk_add_f32 v[96:97], v[96:97], v[100:101]
	v_pk_add_f32 v[100:101], v[90:91], v[102:103]
	v_cvt_pk_bf16_f32 v90, v94, v95
	v_mul_f32_e32 v95, v95, v95
	v_lshlrev_b32_e32 v104, 16, v145
	v_and_b32_e32 v105, 0xffff0000, v145
	v_fmac_f32_e32 v95, v94, v94
	v_mul_f32_e32 v94, v97, v97
	v_pk_add_f32 v[98:99], v[92:93], v[104:105]
	v_fmac_f32_e32 v94, v96, v96
	v_cvt_pk_bf16_f32 v91, v96, v97
	v_add_f32_e32 v94, v95, v94
	v_mul_f32_e32 v95, v101, v101
	v_mul_f32_e32 v96, v99, v99
	v_fmac_f32_e32 v95, v100, v100
	v_fmac_f32_e32 v96, v98, v98
	v_add_f32_e32 v95, v95, v96
	v_add_f32_e32 v102, v94, v95
	s_waitcnt vmcnt(6)
	v_lshlrev_b32_e32 v94, 16, v138
	v_and_b32_e32 v95, 0xffff0000, v138
	v_lshlrev_b32_e32 v96, 16, v139
	v_and_b32_e32 v97, 0xffff0000, v139
	v_cvt_pk_bf16_f32 v93, v98, v99
	v_lshlrev_b32_e32 v98, 16, v140
	v_and_b32_e32 v99, 0xffff0000, v140
	v_pk_add_f32 v[88:89], v[88:89], v[96:97]
	v_pk_add_f32 v[86:87], v[86:87], v[94:95]
	v_cvt_pk_bf16_f32 v92, v100, v101
	v_lshlrev_b32_e32 v100, 16, v141
	v_and_b32_e32 v101, 0xffff0000, v141
	v_pk_add_f32 v[96:97], v[82:83], v[98:99]
	v_mul_f32_e32 v82, v87, v87
	v_mul_f32_e32 v83, v89, v89
	v_pk_add_f32 v[94:95], v[84:85], v[100:101]
	v_fmac_f32_e32 v82, v86, v86
	v_fmac_f32_e32 v83, v88, v88
	v_add_f32_e32 v82, v82, v83
	v_mul_f32_e32 v83, v97, v97
	v_mul_f32_e32 v84, v95, v95
	v_fmac_f32_e32 v83, v96, v96
	v_fmac_f32_e32 v84, v94, v94
	v_add_f32_e32 v83, v83, v84
	v_add_f32_e32 v82, v82, v83
	v_add_f32_e32 v85, v102, v82
	ds_bpermute_b32 v100, v191, v85
	v_lshl_add_u64 v[82:83], s[36:37], 0, v[180:181]
	v_lshl_add_u64 v[98:99], v[168:169], 1, v[82:83]
	v_cvt_pk_bf16_f32 v84, v86, v87
	v_cvt_pk_bf16_f32 v86, v96, v97
	s_waitcnt lgkmcnt(0)
	v_add_f32_e32 v82, v85, v100
	ds_bpermute_b32 v83, v190, v82
	v_cvt_pk_bf16_f32 v85, v88, v89
	v_cvt_pk_bf16_f32 v87, v94, v95
	global_store_dwordx4 v[98:99], v[90:93], off
	global_store_dwordx4 v[98:99], v[84:87], off offset:256
	s_and_saveexec_b64 s[64:65], vcc
	s_cbranch_execz .LBB0_220
	s_waitcnt lgkmcnt(0)
	v_add_f32_e32 v84, v82, v83
	s_lshl_b32 s66, s42, 2
	v_lshlrev_b64 v[82:83], 6, v[178:179]
	s_ashr_i32 s67, s66, 31
	v_lshl_add_u64 v[82:83], s[4:5], 0, v[82:83]
	v_lshl_add_u64 v[82:83], s[66:67], 2, v[82:83]
	s_lshl_b32 s86, s29, 2
	v_lshl_add_u64 v[82:83], v[82:83], 0, s[86:87]
	global_store_dword v[82:83], v84, off
.LBB0_220:
	s_or_b64 exec, exec, s[64:65]
	s_waitcnt vmcnt(7)
	v_lshlrev_b32_e32 v82, 16, v134
	s_waitcnt lgkmcnt(0)
	v_and_b32_e32 v83, 0xffff0000, v134
	v_lshlrev_b32_e32 v84, 16, v135
	v_and_b32_e32 v85, 0xffff0000, v135
	v_lshlrev_b32_e32 v86, 16, v136
	v_and_b32_e32 v87, 0xffff0000, v136
	v_pk_add_f32 v[78:79], v[78:79], v[82:83]
	v_pk_add_f32 v[80:81], v[80:81], v[84:85]
	v_pk_add_f32 v[84:85], v[74:75], v[86:87]
	v_cvt_pk_bf16_f32 v74, v78, v79
	v_mul_f32_e32 v79, v79, v79
	v_lshlrev_b32_e32 v88, 16, v137
	v_and_b32_e32 v89, 0xffff0000, v137
	v_fmac_f32_e32 v79, v78, v78
	v_mul_f32_e32 v78, v81, v81
	v_pk_add_f32 v[82:83], v[76:77], v[88:89]
	v_fmac_f32_e32 v78, v80, v80
	v_cvt_pk_bf16_f32 v75, v80, v81
	v_add_f32_e32 v78, v79, v78
	v_mul_f32_e32 v79, v85, v85
	v_mul_f32_e32 v80, v83, v83
	v_fmac_f32_e32 v79, v84, v84
	v_fmac_f32_e32 v80, v82, v82
	v_add_f32_e32 v79, v79, v80
	v_add_f32_e32 v86, v78, v79
	s_waitcnt vmcnt(6)
	v_lshlrev_b32_e32 v78, 16, v130
	v_and_b32_e32 v79, 0xffff0000, v130
	v_lshlrev_b32_e32 v80, 16, v131
	v_and_b32_e32 v81, 0xffff0000, v131
	v_cvt_pk_bf16_f32 v77, v82, v83
	v_lshlrev_b32_e32 v82, 16, v132
	v_and_b32_e32 v83, 0xffff0000, v132
	v_pk_add_f32 v[72:73], v[72:73], v[80:81]
	v_pk_add_f32 v[70:71], v[70:71], v[78:79]
	v_cvt_pk_bf16_f32 v76, v84, v85
	v_lshlrev_b32_e32 v84, 16, v133
	v_and_b32_e32 v85, 0xffff0000, v133
	v_pk_add_f32 v[80:81], v[66:67], v[82:83]
	v_mul_f32_e32 v66, v71, v71
	v_mul_f32_e32 v67, v73, v73
	v_pk_add_f32 v[78:79], v[68:69], v[84:85]
	v_fmac_f32_e32 v66, v70, v70
	v_fmac_f32_e32 v67, v72, v72
	v_add_f32_e32 v66, v66, v67
	v_mul_f32_e32 v67, v81, v81
	v_mul_f32_e32 v68, v79, v79
	v_fmac_f32_e32 v67, v80, v80
	v_fmac_f32_e32 v68, v78, v78
	v_add_f32_e32 v67, v67, v68
	v_add_f32_e32 v66, v66, v67
	v_add_f32_e32 v69, v86, v66
	ds_bpermute_b32 v84, v191, v69
	v_lshl_add_u64 v[66:67], s[36:37], 0, v[176:177]
	v_lshl_add_u64 v[82:83], v[168:169], 1, v[66:67]
	v_cvt_pk_bf16_f32 v68, v70, v71
	v_cvt_pk_bf16_f32 v70, v80, v81
	s_waitcnt lgkmcnt(0)
	v_add_f32_e32 v66, v69, v84
	ds_bpermute_b32 v67, v190, v66
	v_cvt_pk_bf16_f32 v69, v72, v73
	v_cvt_pk_bf16_f32 v71, v78, v79
	global_store_dwordx4 v[82:83], v[74:77], off
	global_store_dwordx4 v[82:83], v[68:71], off offset:256
	s_and_saveexec_b64 s[64:65], vcc
	s_cbranch_execz .LBB0_222
	s_waitcnt lgkmcnt(0)
	v_add_f32_e32 v68, v66, v67
	s_lshl_b32 s66, s42, 2
	v_lshlrev_b64 v[66:67], 6, v[174:175]
	s_ashr_i32 s67, s66, 31
	v_lshl_add_u64 v[66:67], s[4:5], 0, v[66:67]
	v_lshl_add_u64 v[66:67], s[66:67], 2, v[66:67]
	s_lshl_b32 s86, s29, 2
	v_lshl_add_u64 v[66:67], v[66:67], 0, s[86:87]
	global_store_dword v[66:67], v68, off

; #define PG8_STAGE(bufoff, gbase, voff) do { _Pragma("unroll") for (int _i = 0; _i < 2; ++_i) \
;         __builtin_amdgcn_global_load_lds((const unsigned*)((const char*)(gbase) + (voff)[_i]), (LAS unsigned*)(lds + (bufoff) + ldsw + _i * 8192), 16, 0, 0); } while (0)
; #define PG8_LDA(dst, b, h) do { _Pragma("unroll") for (int m = 0; m < 4; ++m) _Pragma("unroll") for (int k = 0; k < 2; ++k) dst[m][k] = *(const LAS bf16x8*)(lds + PG8_SA(b, h) + aoff + m * 2048 + k * 1024); } while (0)
; #define PG8_LDB(dst, b, h) do { _Pragma("unroll") for (int n = 0; n < 2; ++n) _Pragma("unroll") for (int k = 0; k < 2; ++k) dst[n][k] = *(const LAS bf16x8*)(lds + PG8_SB(b, h) + boff + n * 2048 + k * 1024); } while (0)
; #define PG8_MMA(ai, bj, At, Bt) do { __builtin_amdgcn_s_setprio(1); _Pragma("unroll") for (int m = 0; m < 4; ++m) _Pragma("unroll") for (int n = 0; n < 2; ++n) _Pragma("unroll") for (int k = 0; k < 2; ++k) \
;         acc[ai][bj][m][n] = __builtin_amdgcn_mfma_f32_16x16x32_bf16(Bt[n][k], At[m][k], acc[ai][bj][m][n], 0, 0, 0); __builtin_amdgcn_s_setprio(0); } while (0)
; #define PG8_WAIT_V(n) asm volatile("s_waitcnt vmcnt(" #n ")" ::: "memory")
; #define PG8_WAIT_L(n) asm volatile("s_waitcnt lgkmcnt(" #n ")" ::: "memory")
; #define PG8_BAR __builtin_amdgcn_s_barrier()
; #define PG8_SCHED __builtin_amdgcn_sched_barrier(0)
; template <class Epi>
; __device__ __forceinline__ void gemm_phase(LAS unsigned char* lds, const Gemm g, const StaticOrder& S, const Epi& E) {
;     ...
;             PG8_LDB(B0, 0, 0); PG8_SCHED; PG8_LDA(At, 0, 0); PG8_STAGE(PG8_SA(1, 1), a1 + hA, voffA);
;             PG8_WAIT_L(8); PG8_BAR; PG8_WAIT_L(0); PG8_MMA(0, 0, At, B0); PG8_BAR; PG8_SCHED;
;             PG8_LDB(B1, 0, 1); PG8_STAGE(PG8_SB(0, 0), b2, voffB);
;             PG8_BAR; PG8_WAIT_L(0); PG8_MMA(0, 1, At, B1); PG8_BAR;
;             PG8_LDA(At, 0, 1); PG8_STAGE(PG8_SA(0, 0), a2, voffA);
;             PG8_BAR; PG8_WAIT_L(0); PG8_MMA(1, 0, At, B0); PG8_BAR; PG8_SCHED;
;             PG8_STAGE(PG8_SB(0, 1), b2 + hB, voffB);
;             PG8_WAIT_V(6); PG8_BAR; PG8_MMA(1, 1, At, B1); PG8_BAR;
.LBB0_387:
	s_add_u32 s42, s60, 0x100
	s_addc_u32 s43, s61, 0
	s_add_i32 s22, 0, 0x10000
	v_add_u32_e32 v62, s22, v204
	ds_read_b128 v[38:41], v62
	ds_read_b128 v[46:49], v62 offset:1024
	ds_read_b128 v[54:57], v62 offset:2048
	ds_read_b128 v[62:65], v62 offset:3072
	s_cmp_eq_u32 s97, 4
	s_cselect_b32 s65, s57, s43
	s_cselect_b32 s64, s56, s42
	s_cselect_b32 s63, s49, s55
	s_cselect_b32 s62, s50, s51
	s_add_i32 m0, s68, 0xc000
	ds_read_b128 v[122:125], v205
	ds_read_b128 v[130:133], v205 offset:1024
	ds_read_b128 v[146:149], v205 offset:2048
	ds_read_b128 v[150:153], v205 offset:3072
	ds_read_b128 v[158:161], v205 offset:4096
	ds_read_b128 v[166:169], v205 offset:5120
	ds_read_b128 v[170:173], v205 offset:6144
	ds_read_b128 v[184:187], v205 offset:7168
	global_load_lds_dwordx4 v180, s[60:61]
	s_add_i32 m0, s68, 0xe000
	s_nop 0
	global_load_lds_dwordx4 v182, s[60:61]
	s_waitcnt lgkmcnt(8)
	s_barrier
	s_waitcnt lgkmcnt(0)
	s_setprio 1
	v_mfma_f32_16x16x32_bf16 v[162:165], v[38:41], v[122:125], v[162:165]
	v_mfma_f32_16x16x32_bf16 v[154:157], v[54:57], v[122:125], v[154:157]
	v_mfma_f32_16x16x32_bf16 v[134:137], v[38:41], v[146:149], v[134:137]
	v_mfma_f32_16x16x32_bf16 v[126:129], v[54:57], v[146:149], v[126:129]
	v_mfma_f32_16x16x32_bf16 v[110:113], v[38:41], v[158:161], v[110:113]
	v_mfma_f32_16x16x32_bf16 v[106:109], v[54:57], v[158:161], v[106:109]
	v_mfma_f32_16x16x32_bf16 v[94:97], v[38:41], v[170:173], v[94:97]
	v_mfma_f32_16x16x32_bf16 v[90:93], v[54:57], v[170:173], v[90:93]
	v_mfma_f32_16x16x32_bf16 v[162:165], v[46:49], v[130:133], v[162:165]
	v_mfma_f32_16x16x32_bf16 v[154:157], v[62:65], v[130:133], v[154:157]
	v_mfma_f32_16x16x32_bf16 v[134:137], v[46:49], v[150:153], v[134:137]
	v_mfma_f32_16x16x32_bf16 v[126:129], v[62:65], v[150:153], v[126:129]
	v_mfma_f32_16x16x32_bf16 v[110:113], v[46:49], v[166:169], v[110:113]
	v_mfma_f32_16x16x32_bf16 v[106:109], v[62:65], v[166:169], v[106:109]
	v_mfma_f32_16x16x32_bf16 v[94:97], v[46:49], v[184:187], v[94:97]
	v_mfma_f32_16x16x32_bf16 v[90:93], v[62:65], v[184:187], v[90:93]
	s_setprio 0
	s_barrier
	s_add_i32 s23, 0, 0x14000
	s_add_i32 s22, s22, s67
	v_add_u32_e32 v210, s23, v204
	s_mov_b32 m0, s22
	ds_read_b128 v[188:191], v210
	ds_read_b128 v[192:195], v210 offset:1024
	ds_read_b128 v[206:209], v210 offset:2048
	ds_read_b128 v[210:213], v210 offset:3072
	global_load_lds_dwordx4 v0, s[62:63]
	s_add_i32 m0, s22, 0x2000
	s_nop 0
	global_load_lds_dwordx4 v178, s[62:63]
	s_barrier
	s_waitcnt lgkmcnt(0)
	s_setprio 1
	v_mfma_f32_16x16x32_bf16 v[142:145], v[188:191], v[122:125], v[142:145]
	v_mfma_f32_16x16x32_bf16 v[118:121], v[188:191], v[146:149], v[118:121]
	v_mfma_f32_16x16x32_bf16 v[114:117], v[206:209], v[146:149], v[114:117]
	v_mfma_f32_16x16x32_bf16 v[102:105], v[188:191], v[158:161], v[102:105]
	v_mfma_f32_16x16x32_bf16 v[98:101], v[206:209], v[158:161], v[98:101]
	v_mfma_f32_16x16x32_bf16 v[86:89], v[188:191], v[170:173], v[86:89]
	v_mfma_f32_16x16x32_bf16 v[82:85], v[206:209], v[170:173], v[82:85]
	v_mfma_f32_16x16x32_bf16 v[142:145], v[192:195], v[130:133], v[142:145]
	v_mfma_f32_16x16x32_bf16 v[122:125], v[206:209], v[122:125], v[138:141]
	v_mfma_f32_16x16x32_bf16 v[118:121], v[192:195], v[150:153], v[118:121]
	v_mfma_f32_16x16x32_bf16 v[114:117], v[210:213], v[150:153], v[114:117]
	v_mfma_f32_16x16x32_bf16 v[102:105], v[192:195], v[166:169], v[102:105]
	v_mfma_f32_16x16x32_bf16 v[98:101], v[210:213], v[166:169], v[98:101]
	v_mfma_f32_16x16x32_bf16 v[86:89], v[192:195], v[184:187], v[86:89]
	v_mfma_f32_16x16x32_bf16 v[82:85], v[210:213], v[184:187], v[82:85]
	v_mfma_f32_16x16x32_bf16 v[122:125], v[210:213], v[130:133], v[122:125]
	s_setprio 0
	s_mov_b32 m0, s68
	s_barrier
	ds_read_b128 v[130:133], v205 offset:16384
	ds_read_b128 v[138:141], v205 offset:17408
	ds_read_b128 v[146:149], v205 offset:18432
	ds_read_b128 v[150:153], v205 offset:19456
	ds_read_b128 v[158:161], v205 offset:20480
	ds_read_b128 v[166:169], v205 offset:21504
	ds_read_b128 v[170:173], v205 offset:22528
	ds_read_b128 v[184:187], v205 offset:23552
	global_load_lds_dwordx4 v174, s[64:65]
	s_mov_b32 m0, s69
	s_nop 0
	global_load_lds_dwordx4 v176, s[64:65]
	s_barrier
	s_waitcnt lgkmcnt(0)
	s_setprio 1
	v_mfma_f32_16x16x32_bf16 v[78:81], v[38:41], v[130:133], v[78:81]
	v_mfma_f32_16x16x32_bf16 v[74:77], v[54:57], v[130:133], v[74:77]
	v_mfma_f32_16x16x32_bf16 v[58:61], v[38:41], v[146:149], v[58:61]
	v_mfma_f32_16x16x32_bf16 v[50:53], v[54:57], v[146:149], v[50:53]
	v_mfma_f32_16x16x32_bf16 v[30:33], v[38:41], v[158:161], v[30:33]
	v_mfma_f32_16x16x32_bf16 v[26:29], v[54:57], v[158:161], v[26:29]
	v_mfma_f32_16x16x32_bf16 v[14:17], v[38:41], v[170:173], v[14:17]
	v_mfma_f32_16x16x32_bf16 v[10:13], v[54:57], v[170:173], v[10:13]
	v_mfma_f32_16x16x32_bf16 v[78:81], v[46:49], v[138:141], v[78:81]
	v_mfma_f32_16x16x32_bf16 v[74:77], v[62:65], v[138:141], v[74:77]
	v_mfma_f32_16x16x32_bf16 v[58:61], v[46:49], v[150:153], v[58:61]
	v_mfma_f32_16x16x32_bf16 v[50:53], v[62:65], v[150:153], v[50:53]
	v_mfma_f32_16x16x32_bf16 v[30:33], v[46:49], v[166:169], v[30:33]
	v_mfma_f32_16x16x32_bf16 v[26:29], v[62:65], v[166:169], v[26:29]
	v_mfma_f32_16x16x32_bf16 v[14:17], v[46:49], v[184:187], v[14:17]
	v_mfma_f32_16x16x32_bf16 v[10:13], v[62:65], v[184:187], v[10:13]
	s_setprio 0
	s_barrier
	s_add_u32 s60, s62, 0x20000
	s_addc_u32 s61, s63, 0
	s_add_i32 s22, s23, s67
	s_mov_b32 m0, s22
	s_nop 0
	global_load_lds_dwordx4 v0, s[60:61]
	s_add_i32 m0, s22, 0x2000
	s_nop 0
	global_load_lds_dwordx4 v178, s[60:61]
	s_waitcnt vmcnt(6)
	s_barrier
; #define PG8_STAGE(bufoff, gbase, voff) do { _Pragma("unroll") for (int _i = 0; _i < 2; ++_i) \
;         __builtin_amdgcn_global_load_lds((const unsigned*)((const char*)(gbase) + (voff)[_i]), (LAS unsigned*)(lds + (bufoff) + ldsw + _i * 8192), 16, 0, 0); } while (0)
; #define PG8_LDA(dst, b, h) do { _Pragma("unroll") for (int m = 0; m < 4; ++m) _Pragma("unroll") for (int k = 0; k < 2; ++k) dst[m][k] = *(const LAS bf16x8*)(lds + PG8_SA(b, h) + aoff + m * 2048 + k * 1024); } while (0)
; #define PG8_LDB(dst, b, h) do { _Pragma("unroll") for (int n = 0; n < 2; ++n) _Pragma("unroll") for (int k = 0; k < 2; ++k) dst[n][k] = *(const LAS bf16x8*)(lds + PG8_SB(b, h) + boff + n * 2048 + k * 1024); } while (0)
; #define PG8_MMA(ai, bj, At, Bt) do { __builtin_amdgcn_s_setprio(1); _Pragma("unroll") for (int m = 0; m < 4; ++m) _Pragma("unroll") for (int n = 0; n < 2; ++n) _Pragma("unroll") for (int k = 0; k < 2; ++k) \
;         acc[ai][bj][m][n] = __builtin_amdgcn_mfma_f32_16x16x32_bf16(Bt[n][k], At[m][k], acc[ai][bj][m][n], 0, 0, 0); __builtin_amdgcn_s_setprio(0); } while (0)
; #define PG8_WAIT_V(n) asm volatile("s_waitcnt vmcnt(" #n ")" ::: "memory")
; #define PG8_WAIT_L(n) asm volatile("s_waitcnt lgkmcnt(" #n ")" ::: "memory")
; #define PG8_BAR __builtin_amdgcn_s_barrier()
; #define PG8_SCHED __builtin_amdgcn_sched_barrier(0)
; template <class Epi>
; __device__ __forceinline__ void gemm_phase(LAS unsigned char* lds, const Gemm g, const StaticOrder& S, const Epi& E) {
;     ...
;             PG8_WAIT_V(6); PG8_BAR; PG8_MMA(1, 1, At, B1); PG8_BAR;
;             PG8_LDB(B0, 1, 0); PG8_SCHED; PG8_LDA(At, 1, 0); PG8_STAGE(PG8_SA(0, 1), a2 + hA, voffA);
;             PG8_WAIT_L(8); PG8_BAR; PG8_WAIT_L(0); PG8_MMA(0, 0, At, B0); PG8_BAR; PG8_SCHED;
;             PG8_LDB(B1, 1, 1); PG8_STAGE(PG8_SB(1, 0), b3, voffB);
;             PG8_BAR; PG8_WAIT_L(0); PG8_MMA(0, 1, At, B1); PG8_BAR;
;             PG8_LDA(At, 1, 1); PG8_STAGE(PG8_SA(1, 0), a3, voffA);
	s_setprio 1
	v_mfma_f32_16x16x32_bf16 v[42:45], v[188:191], v[146:149], v[42:45]
	v_mfma_f32_16x16x32_bf16 v[34:37], v[206:209], v[146:149], v[34:37]
	v_mfma_f32_16x16x32_bf16 v[22:25], v[188:191], v[158:161], v[22:25]
	v_mfma_f32_16x16x32_bf16 v[18:21], v[206:209], v[158:161], v[18:21]
	v_mfma_f32_16x16x32_bf16 v[6:9], v[188:191], v[170:173], v[6:9]
	v_mfma_f32_16x16x32_bf16 v[2:5], v[206:209], v[170:173], v[2:5]
	v_mfma_f32_16x16x32_bf16 v[38:41], v[188:191], v[130:133], v[70:73]
	v_mfma_f32_16x16x32_bf16 v[46:49], v[206:209], v[130:133], v[66:69]
	v_mfma_f32_16x16x32_bf16 v[42:45], v[192:195], v[150:153], v[42:45]
	v_mfma_f32_16x16x32_bf16 v[34:37], v[210:213], v[150:153], v[34:37]
	v_mfma_f32_16x16x32_bf16 v[22:25], v[192:195], v[166:169], v[22:25]
	v_mfma_f32_16x16x32_bf16 v[18:21], v[210:213], v[166:169], v[18:21]
	v_mfma_f32_16x16x32_bf16 v[6:9], v[192:195], v[184:187], v[6:9]
	v_mfma_f32_16x16x32_bf16 v[2:5], v[210:213], v[184:187], v[2:5]
	v_mfma_f32_16x16x32_bf16 v[38:41], v[192:195], v[138:141], v[38:41]
	v_mfma_f32_16x16x32_bf16 v[46:49], v[210:213], v[138:141], v[46:49]
	s_setprio 0
	s_add_i32 s22, 0, 0x18000
	v_add_u32_e32 v70, s22, v204
	s_barrier
	ds_read_b128 v[54:57], v70
	ds_read_b128 v[62:65], v70 offset:1024
	ds_read_b128 v[66:69], v70 offset:2048
	ds_read_b128 v[70:73], v70 offset:3072
	s_add_u32 s60, s64, 0x110000
	s_addc_u32 s61, s65, 0
	s_mov_b32 m0, s70
	ds_read_b128 v[130:133], v205 offset:32768
	ds_read_b128 v[138:141], v205 offset:33792
	ds_read_b128 v[146:149], v205 offset:34816
	ds_read_b128 v[150:153], v205 offset:35840
	ds_read_b128 v[158:161], v205 offset:36864
	ds_read_b128 v[166:169], v205 offset:37888
	ds_read_b128 v[170:173], v205 offset:38912
	ds_read_b128 v[184:187], v205 offset:39936
	global_load_lds_dwordx4 v174, s[60:61]
	s_mov_b32 m0, s71
	s_nop 0
	global_load_lds_dwordx4 v176, s[60:61]
	s_waitcnt lgkmcnt(8)
	s_barrier
	s_waitcnt lgkmcnt(0)
	s_setprio 1
	v_mfma_f32_16x16x32_bf16 v[162:165], v[54:57], v[130:133], v[162:165]
	v_mfma_f32_16x16x32_bf16 v[154:157], v[66:69], v[130:133], v[154:157]
	v_mfma_f32_16x16x32_bf16 v[134:137], v[54:57], v[146:149], v[134:137]
	v_mfma_f32_16x16x32_bf16 v[126:129], v[66:69], v[146:149], v[126:129]
	v_mfma_f32_16x16x32_bf16 v[110:113], v[54:57], v[158:161], v[110:113]
	v_mfma_f32_16x16x32_bf16 v[106:109], v[66:69], v[158:161], v[106:109]
	v_mfma_f32_16x16x32_bf16 v[94:97], v[54:57], v[170:173], v[94:97]
	v_mfma_f32_16x16x32_bf16 v[90:93], v[66:69], v[170:173], v[90:93]
	v_mfma_f32_16x16x32_bf16 v[162:165], v[62:65], v[138:141], v[162:165]
	v_mfma_f32_16x16x32_bf16 v[154:157], v[70:73], v[138:141], v[154:157]
	v_mfma_f32_16x16x32_bf16 v[134:137], v[62:65], v[150:153], v[134:137]
	v_mfma_f32_16x16x32_bf16 v[126:129], v[70:73], v[150:153], v[126:129]
	v_mfma_f32_16x16x32_bf16 v[110:113], v[62:65], v[166:169], v[110:113]
	v_mfma_f32_16x16x32_bf16 v[106:109], v[70:73], v[166:169], v[106:109]
	v_mfma_f32_16x16x32_bf16 v[94:97], v[62:65], v[184:187], v[94:97]
	v_mfma_f32_16x16x32_bf16 v[90:93], v[70:73], v[184:187], v[90:93]
	s_setprio 0
	s_barrier
	s_add_i32 s23, 0, 0x1c000
	s_add_i32 s22, s22, s67
	v_add_u32_e32 v210, s23, v204
	s_mov_b32 m0, s22
	ds_read_b128 v[188:191], v210
	ds_read_b128 v[192:195], v210 offset:1024
	ds_read_b128 v[206:209], v210 offset:2048
	ds_read_b128 v[210:213], v210 offset:3072
	s_add_u32 s100, s62, 0x80
	s_addc_u32 s101, s63, 0
	global_load_lds_dwordx4 v0, s[100:101]
	s_add_i32 m0, s22, 0x2000
	s_nop 0
	global_load_lds_dwordx4 v178, s[100:101]
	s_barrier
	s_waitcnt lgkmcnt(0)
	s_setprio 1
	v_mfma_f32_16x16x32_bf16 v[142:145], v[188:191], v[130:133], v[142:145]
	v_mfma_f32_16x16x32_bf16 v[122:125], v[206:209], v[130:133], v[122:125]
	v_mfma_f32_16x16x32_bf16 v[118:121], v[188:191], v[146:149], v[118:121]
	v_mfma_f32_16x16x32_bf16 v[114:117], v[206:209], v[146:149], v[114:117]
	v_mfma_f32_16x16x32_bf16 v[102:105], v[188:191], v[158:161], v[102:105]
	v_mfma_f32_16x16x32_bf16 v[98:101], v[206:209], v[158:161], v[98:101]
	v_mfma_f32_16x16x32_bf16 v[86:89], v[188:191], v[170:173], v[86:89]
	v_mfma_f32_16x16x32_bf16 v[82:85], v[206:209], v[170:173], v[82:85]
	v_mfma_f32_16x16x32_bf16 v[142:145], v[192:195], v[138:141], v[142:145]
	v_mfma_f32_16x16x32_bf16 v[138:141], v[210:213], v[138:141], v[122:125]
	v_mfma_f32_16x16x32_bf16 v[118:121], v[192:195], v[150:153], v[118:121]
	v_mfma_f32_16x16x32_bf16 v[114:117], v[210:213], v[150:153], v[114:117]
	v_mfma_f32_16x16x32_bf16 v[102:105], v[192:195], v[166:169], v[102:105]
	v_mfma_f32_16x16x32_bf16 v[98:101], v[210:213], v[166:169], v[98:101]
	v_mfma_f32_16x16x32_bf16 v[86:89], v[192:195], v[184:187], v[86:89]
	v_mfma_f32_16x16x32_bf16 v[82:85], v[210:213], v[184:187], v[82:85]
	s_setprio 0
	s_mov_b32 m0, s75
	s_barrier
	ds_read_b128 v[122:125], v205 offset:49152
	ds_read_b128 v[130:133], v205 offset:50176
	ds_read_b128 v[146:149], v205 offset:51200
	ds_read_b128 v[150:153], v205 offset:52224
	ds_read_b128 v[158:161], v205 offset:53248
	ds_read_b128 v[166:169], v205 offset:54272
	ds_read_b128 v[170:173], v205 offset:55296
	ds_read_b128 v[184:187], v205 offset:56320
	s_add_u32 s100, s64, 0x80
	s_addc_u32 s101, s65, 0
	global_load_lds_dwordx4 v174, s[100:101]
	s_mov_b32 m0, s76
	s_nop 0
	global_load_lds_dwordx4 v176, s[100:101]
	s_barrier
; #define PG8_STAGE(bufoff, gbase, voff) do { _Pragma("unroll") for (int _i = 0; _i < 2; ++_i) \
;         __builtin_amdgcn_global_load_lds((const unsigned*)((const char*)(gbase) + (voff)[_i]), (LAS unsigned*)(lds + (bufoff) + ldsw + _i * 8192), 16, 0, 0); } while (0)
; #define PG8_MMA(ai, bj, At, Bt) do { __builtin_amdgcn_s_setprio(1); _Pragma("unroll") for (int m = 0; m < 4; ++m) _Pragma("unroll") for (int n = 0; n < 2; ++n) _Pragma("unroll") for (int k = 0; k < 2; ++k) \
;         acc[ai][bj][m][n] = __builtin_amdgcn_mfma_f32_16x16x32_bf16(Bt[n][k], At[m][k], acc[ai][bj][m][n], 0, 0, 0); __builtin_amdgcn_s_setprio(0); } while (0)
; #define PG8_WAIT_V(n) asm volatile("s_waitcnt vmcnt(" #n ")" ::: "memory")
; #define PG8_BAR __builtin_amdgcn_s_barrier()
; template <class Epi>
; __device__ __forceinline__ void gemm_phase(LAS unsigned char* lds, const Gemm g, const StaticOrder& S, const Epi& E) {
;     ...
;             PG8_BAR; PG8_WAIT_L(0); PG8_MMA(1, 0, At, B0); PG8_BAR; PG8_SCHED;
;             PG8_STAGE(PG8_SB(1, 1), b3 + hB, voffB);
;             PG8_WAIT_V(6); PG8_BAR; PG8_MMA(1, 1, At, B1); PG8_BAR;
;         }
;         if constexpr (Epi::HAS_PRE) { E(acc, cur, wr, wc, fr, fq, pre); if (has_next) E.pre(pre, nxt, wr, fr); } else E(acc, cur, wr, wc, fr, fq);
;     __device__ __forceinline__ void operator()(const Acc& acc, const Unit& u, int wr, int wc, int fr, int fq) const {
;     ...
;         const int row0 = u.pm * 256 + wr * 64 + fr, col0 = u.pn * 256 + wc * 32 + 8 * fq;
;         f32x4 bv[2][2];
; #pragma unroll
;         for (int bj = 0; bj < 2; ++bj)
; #pragma unroll
;             for (int n = 0; n < 2; ++n) bv[bj][n] = *(const f32x4*)(bias + col0 + bj * 128 + 4 * n);
; #pragma unroll
;         for (int ai = 0; ai < 2; ++ai) {
;             u32x4 av[4][2];
; #pragma unroll
;             for (int m = 0; m < 4; ++m)
; #pragma unroll
;                 for (int bj = 0; bj < 2; ++bj) av[m][bj] = *(const u32x4*)(proj + (size_t)(row0 + ai * 128 + m * 16) * NPROJ + col0 + bj * 128);
; #pragma unroll
;             for (int m = 0; m < 4; ++m) { bf16_t* rowp = proj + (size_t)(row0 + ai * 128 + m * 16) * NPROJ + col0;
; #pragma unroll
;                 for (int bj = 0; bj < 2; ++bj) { f32x4 a0, a1; unpack8(av[m][bj], a0, a1);
;                     const f32x4 o0 = a0 * sig4(acc[ai][bj][m][0] + bv[bj][0]), o1 = a1 * sig4(acc[ai][bj][m][1] + bv[bj][1]);
	s_waitcnt lgkmcnt(0)
	s_setprio 1
	v_mfma_f32_16x16x32_bf16 v[78:81], v[54:57], v[122:125], v[78:81]
	v_mfma_f32_16x16x32_bf16 v[74:77], v[66:69], v[122:125], v[74:77]
	v_mfma_f32_16x16x32_bf16 v[58:61], v[54:57], v[146:149], v[58:61]
	v_mfma_f32_16x16x32_bf16 v[50:53], v[66:69], v[146:149], v[50:53]
	v_mfma_f32_16x16x32_bf16 v[30:33], v[54:57], v[158:161], v[30:33]
	v_mfma_f32_16x16x32_bf16 v[26:29], v[66:69], v[158:161], v[26:29]
	v_mfma_f32_16x16x32_bf16 v[14:17], v[54:57], v[170:173], v[14:17]
	v_mfma_f32_16x16x32_bf16 v[10:13], v[66:69], v[170:173], v[10:13]
	v_mfma_f32_16x16x32_bf16 v[78:81], v[62:65], v[130:133], v[78:81]
	v_mfma_f32_16x16x32_bf16 v[74:77], v[70:73], v[130:133], v[74:77]
	v_mfma_f32_16x16x32_bf16 v[58:61], v[62:65], v[150:153], v[58:61]
	v_mfma_f32_16x16x32_bf16 v[50:53], v[70:73], v[150:153], v[50:53]
	v_mfma_f32_16x16x32_bf16 v[30:33], v[62:65], v[166:169], v[30:33]
	v_mfma_f32_16x16x32_bf16 v[26:29], v[70:73], v[166:169], v[26:29]
	v_mfma_f32_16x16x32_bf16 v[14:17], v[62:65], v[184:187], v[14:17]
	v_mfma_f32_16x16x32_bf16 v[10:13], v[70:73], v[184:187], v[10:13]
	s_setprio 0
	s_barrier
	s_add_u32 s60, s62, 0x20080
	s_addc_u32 s61, s63, 0
	s_add_i32 s22, s23, s67
	s_mov_b32 m0, s22
	s_nop 0
	global_load_lds_dwordx4 v0, s[60:61]
	s_add_i32 m0, s22, 0x2000
	s_nop 0
	global_load_lds_dwordx4 v178, s[60:61]
	s_waitcnt vmcnt(6)
	s_barrier
	s_setprio 1
	v_mfma_f32_16x16x32_bf16 v[38:41], v[188:191], v[122:125], v[38:41]
	v_mfma_f32_16x16x32_bf16 v[70:73], v[192:195], v[130:133], v[38:41]
	v_mfma_f32_16x16x32_bf16 v[38:41], v[206:209], v[122:125], v[46:49]
	v_mfma_f32_16x16x32_bf16 v[66:69], v[210:213], v[130:133], v[38:41]
	v_mfma_f32_16x16x32_bf16 v[38:41], v[188:191], v[146:149], v[42:45]
	v_mfma_f32_16x16x32_bf16 v[34:37], v[206:209], v[146:149], v[34:37]
	v_mfma_f32_16x16x32_bf16 v[22:25], v[188:191], v[158:161], v[22:25]
	v_mfma_f32_16x16x32_bf16 v[18:21], v[206:209], v[158:161], v[18:21]
	v_mfma_f32_16x16x32_bf16 v[6:9], v[188:191], v[170:173], v[6:9]
	v_mfma_f32_16x16x32_bf16 v[2:5], v[206:209], v[170:173], v[2:5]
	v_mfma_f32_16x16x32_bf16 v[42:45], v[192:195], v[150:153], v[38:41]
	v_mfma_f32_16x16x32_bf16 v[34:37], v[210:213], v[150:153], v[34:37]
	v_mfma_f32_16x16x32_bf16 v[22:25], v[192:195], v[166:169], v[22:25]
	v_mfma_f32_16x16x32_bf16 v[18:21], v[210:213], v[166:169], v[18:21]
	v_mfma_f32_16x16x32_bf16 v[6:9], v[192:195], v[184:187], v[6:9]
	v_mfma_f32_16x16x32_bf16 v[2:5], v[210:213], v[184:187], v[2:5]
	s_setprio 0
	s_add_i32 s97, s97, 2
	s_add_u32 s51, s51, 0x100
	s_addc_u32 s55, s55, 0
	s_cmp_gt_u32 s97, 5
	s_mov_b64 s[60:61], s[42:43]
	s_barrier
	s_cbranch_scc0 .LBB0_387
	s_lshl_b32 s23, s48, 8
	v_mov_b32_e32 v38, v203
	v_mov_b32_e32 v124, v202
	s_or_b32 s23, s23, s74
	s_lshl_b32 s22, s33, 8
	v_lshl_add_u32 v122, v38, 3, s23
	v_ashrrev_i32_e32 v123, 31, v122
	v_lshl_add_u64 v[46:47], v[122:123], 2, s[2:3]
	global_load_dwordx4 v[54:57], v[46:47], off offset:16
	global_load_dwordx4 v[62:65], v[46:47], off
	global_load_dwordx4 v[38:41], v[46:47], off offset:528
	s_nop 0
	global_load_dwordx4 v[46:49], v[46:47], off offset:512
	s_add_i32 s22, s22, s30
	v_lshlrev_b64 v[184:185], 1, v[122:123]
	v_add_u32_e32 v206, s22, v124
	v_lshl_add_u64 v[188:189], s[20:21], 0, v[184:185]
	v_mad_i64_i32 v[122:123], s[42:43], v206, s96, v[188:189]
	global_load_dwordx4 v[192:195], v[122:123], off
	global_load_dwordx4 v[170:173], v[122:123], off offset:256
	v_add_u32_e32 v209, 16, v206
	v_mad_i64_i32 v[122:123], s[42:43], v209, s96, v[188:189]
	global_load_dwordx4 v[166:169], v[122:123], off
	global_load_dwordx4 v[158:161], v[122:123], off offset:256
	v_add_u32_e32 v208, 32, v206
	v_mad_i64_i32 v[122:123], s[42:43], v208, s96, v[188:189]
	global_load_dwordx4 v[150:153], v[122:123], off
	global_load_dwordx4 v[146:149], v[122:123], off offset:256
	v_add_u32_e32 v207, 48, v206
	v_mad_i64_i32 v[122:123], s[42:43], v207, s96, v[188:189]
	global_load_dwordx4 v[130:133], v[122:123], off
	s_nop 0
	global_load_dwordx4 v[122:125], v[122:123], off offset:256
	v_mov_b64_e32 v[186:187], s[20:21]
	v_mad_i64_i32 v[190:191], s[42:43], v206, s96, v[186:187]
	v_lshl_add_u64 v[190:191], v[190:191], 0, v[184:185]
	s_and_b64 vcc, exec, s[40:41]
	s_mov_b32 s48, s54
	s_mov_b32 s33, s47
	s_mov_b64 s[62:63], s[58:59]
	s_mov_b64 s[60:61], s[56:57]
	s_waitcnt vmcnt(11)
	v_pk_add_f32 v[156:157], v[156:157], v[56:57]
	s_waitcnt vmcnt(10)
	v_pk_add_f32 v[164:165], v[164:165], v[64:65]
	v_pk_add_f32 v[162:163], v[162:163], v[62:63]
	v_pk_add_f32 v[154:155], v[154:155], v[54:55]
	v_mul_f32_e32 v162, 0xbfb8aa3b, v162
	v_mul_f32_e32 v163, 0xbfb8aa3b, v163
	v_mul_f32_e32 v164, 0xbfb8aa3b, v164
	v_mul_f32_e32 v165, 0xbfb8aa3b, v165
	v_mul_f32_e32 v154, 0xbfb8aa3b, v154
	v_mul_f32_e32 v155, 0xbfb8aa3b, v155
	v_mul_f32_e32 v156, 0xbfb8aa3b, v156
	v_mul_f32_e32 v157, 0xbfb8aa3b, v157
	v_exp_f32_e32 v162, v162
	v_exp_f32_e32 v163, v163
	v_exp_f32_e32 v164, v164
	v_exp_f32_e32 v165, v165
	v_exp_f32_e32 v154, v154
	v_exp_f32_e32 v155, v155
	v_exp_f32_e32 v156, v156
	v_exp_f32_e32 v157, v157
	s_waitcnt vmcnt(8)
; __device__ __forceinline__ u32x4 pack8(const f32x4 a, const f32x4 b) { u32x4 w; w.x = cvt_pk_bf16(a[0], a[1]); w.y = cvt_pk_bf16(a[2], a[3]); w.z = cvt_pk_bf16(b[0], b[1]); w.w = cvt_pk_bf16(b[2], b[3]); return w; }
; __device__ __forceinline__ void unpack8(const u32x4 w, f32x4& a, f32x4& b) { a = (f32x4){bflo(w.x), bfhi(w.x), bflo(w.y), bfhi(w.y)}; b = (f32x4){bflo(w.z), bfhi(w.z), bflo(w.w), bfhi(w.w)}; }
; __device__ __forceinline__ f32x4 sig4(const f32x4 v) { return (f32x4){sigmoidf_(v[0]), sigmoidf_(v[1]), sigmoidf_(v[2]), sigmoidf_(v[3])}; }
;     __device__ __forceinline__ void operator()(const Acc& acc, const Unit& u, int wr, int wc, int fr, int fq) const {
;     ...
;         for (int ai = 0; ai < 2; ++ai) {
;             u32x4 av[4][2];
; #pragma unroll
;             for (int m = 0; m < 4; ++m)
; #pragma unroll
;                 for (int bj = 0; bj < 2; ++bj) av[m][bj] = *(const u32x4*)(proj + (size_t)(row0 + ai * 128 + m * 16) * NPROJ + col0 + bj * 128);
; #pragma unroll
;             for (int m = 0; m < 4; ++m) { bf16_t* rowp = proj + (size_t)(row0 + ai * 128 + m * 16) * NPROJ + col0;
; #pragma unroll
;                 for (int bj = 0; bj < 2; ++bj) { f32x4 a0, a1; unpack8(av[m][bj], a0, a1);
;                     const f32x4 o0 = a0 * sig4(acc[ai][bj][m][0] + bv[bj][0]), o1 = a1 * sig4(acc[ai][bj][m][1] + bv[bj][1]);
;                     *(u32x4*)(rowp + C_GLU + bj * 128) = pack8(o0, o1); } } }
	v_pk_add_f32 v[144:145], v[144:145], v[48:49]
	v_pk_add_f32 v[142:143], v[142:143], v[46:47]
	v_pk_add_f32 v[140:141], v[140:141], v[40:41]
	v_pk_add_f32 v[138:139], v[138:139], v[38:39]
	v_mul_f32_e32 v142, 0xbfb8aa3b, v142
	v_mul_f32_e32 v143, 0xbfb8aa3b, v143
	v_mul_f32_e32 v144, 0xbfb8aa3b, v144
	v_mul_f32_e32 v145, 0xbfb8aa3b, v145
	v_mul_f32_e32 v138, 0xbfb8aa3b, v138
	v_mul_f32_e32 v139, 0xbfb8aa3b, v139
	v_mul_f32_e32 v140, 0xbfb8aa3b, v140
	v_mul_f32_e32 v141, 0xbfb8aa3b, v141
	v_exp_f32_e32 v142, v142
	v_exp_f32_e32 v143, v143
	v_exp_f32_e32 v144, v144
	v_exp_f32_e32 v145, v145
	v_exp_f32_e32 v138, v138
	v_exp_f32_e32 v139, v139
	v_exp_f32_e32 v140, v140
	v_exp_f32_e32 v141, v141
	v_add_f32_e32 v162, 1.0, v162
	v_add_f32_e32 v163, 1.0, v163
	v_add_f32_e32 v164, 1.0, v164
	v_add_f32_e32 v165, 1.0, v165
	v_add_f32_e32 v154, 1.0, v154
	v_add_f32_e32 v155, 1.0, v155
	v_add_f32_e32 v156, 1.0, v156
	v_add_f32_e32 v157, 1.0, v157
	v_pk_add_f32 v[136:137], v[136:137], v[64:65]
	v_pk_add_f32 v[134:135], v[134:135], v[62:63]
	v_pk_add_f32 v[128:129], v[128:129], v[56:57]
	v_pk_add_f32 v[126:127], v[126:127], v[54:55]
	v_rcp_f32_e32 v162, v162
	v_rcp_f32_e32 v163, v163
	v_rcp_f32_e32 v164, v164
	v_rcp_f32_e32 v165, v165
	v_rcp_f32_e32 v154, v154
	v_rcp_f32_e32 v155, v155
	v_rcp_f32_e32 v156, v156
	v_rcp_f32_e32 v157, v157
	v_mul_f32_e32 v134, 0xbfb8aa3b, v134
	v_mul_f32_e32 v135, 0xbfb8aa3b, v135
	v_mul_f32_e32 v136, 0xbfb8aa3b, v136
	v_mul_f32_e32 v137, 0xbfb8aa3b, v137
	v_mul_f32_e32 v126, 0xbfb8aa3b, v126
	v_mul_f32_e32 v127, 0xbfb8aa3b, v127
	v_mul_f32_e32 v128, 0xbfb8aa3b, v128
	v_mul_f32_e32 v129, 0xbfb8aa3b, v129
	v_exp_f32_e32 v134, v134
	v_exp_f32_e32 v135, v135
	v_exp_f32_e32 v136, v136
	v_exp_f32_e32 v137, v137
	v_exp_f32_e32 v126, v126
	v_exp_f32_e32 v127, v127
	v_exp_f32_e32 v128, v128
	v_exp_f32_e32 v129, v129
	v_add_f32_e32 v142, 1.0, v142
	v_add_f32_e32 v143, 1.0, v143
	v_add_f32_e32 v144, 1.0, v144
	v_add_f32_e32 v145, 1.0, v145
	v_add_f32_e32 v138, 1.0, v138
	v_add_f32_e32 v139, 1.0, v139
	v_add_f32_e32 v140, 1.0, v140
	v_add_f32_e32 v141, 1.0, v141
	v_pk_add_f32 v[120:121], v[120:121], v[48:49]
	v_pk_add_f32 v[118:119], v[118:119], v[46:47]
	v_pk_add_f32 v[116:117], v[116:117], v[40:41]
	v_pk_add_f32 v[114:115], v[114:115], v[38:39]
	s_waitcnt vmcnt(7)
	v_lshlrev_b32_e32 v210, 16, v192
	v_and_b32_e32 v211, 0xffff0000, v192
	v_lshlrev_b32_e32 v212, 16, v193
	v_and_b32_e32 v213, 0xffff0000, v193
	v_lshlrev_b32_e32 v192, 16, v194
	v_and_b32_e32 v193, 0xffff0000, v194
	v_lshlrev_b32_e32 v194, 16, v195
	v_and_b32_e32 v195, 0xffff0000, v195
	v_rcp_f32_e32 v142, v142
	v_rcp_f32_e32 v143, v143
	v_rcp_f32_e32 v144, v144
	v_rcp_f32_e32 v145, v145
	v_rcp_f32_e32 v138, v138
	v_rcp_f32_e32 v139, v139
	v_rcp_f32_e32 v140, v140
	v_rcp_f32_e32 v141, v141
	v_mul_f32_e32 v118, 0xbfb8aa3b, v118
	v_mul_f32_e32 v119, 0xbfb8aa3b, v119
	v_mul_f32_e32 v120, 0xbfb8aa3b, v120
	v_mul_f32_e32 v121, 0xbfb8aa3b, v121
	v_mul_f32_e32 v114, 0xbfb8aa3b, v114
	v_mul_f32_e32 v115, 0xbfb8aa3b, v115
	v_mul_f32_e32 v116, 0xbfb8aa3b, v116
	v_mul_f32_e32 v117, 0xbfb8aa3b, v117
	v_pk_mul_f32 v[164:165], v[164:165], v[212:213]
	v_pk_mul_f32 v[162:163], v[162:163], v[210:211]
	v_pk_mul_f32 v[194:195], v[156:157], v[194:195]
	v_pk_mul_f32 v[156:157], v[154:155], v[192:193]
	v_exp_f32_e32 v118, v118
	v_exp_f32_e32 v119, v119
	v_exp_f32_e32 v120, v120
	v_exp_f32_e32 v121, v121
	v_exp_f32_e32 v114, v114
	v_exp_f32_e32 v115, v115
	v_exp_f32_e32 v116, v116
	v_exp_f32_e32 v117, v117
	v_cvt_pk_bf16_f32 v154, v162, v163
	v_cvt_pk_bf16_f32 v155, v164, v165
	v_cvt_pk_bf16_f32 v156, v156, v157
	v_cvt_pk_bf16_f32 v157, v194, v195
	v_add_f32_e32 v134, 1.0, v134
	v_add_f32_e32 v135, 1.0, v135
	v_add_f32_e32 v136, 1.0, v136
	v_add_f32_e32 v137, 1.0, v137
	v_add_f32_e32 v126, 1.0, v126
	v_add_f32_e32 v127, 1.0, v127
	v_add_f32_e32 v128, 1.0, v128
	v_add_f32_e32 v129, 1.0, v129
	v_pk_add_f32 v[112:113], v[112:113], v[64:65]
	v_pk_add_f32 v[110:111], v[110:111], v[62:63]
	v_pk_add_f32 v[108:109], v[108:109], v[56:57]
	v_pk_add_f32 v[106:107], v[106:107], v[54:55]
	global_store_dwordx4 v[190:191], v[154:157], off offset:1024
	s_waitcnt vmcnt(7)
	v_lshlrev_b32_e32 v162, 16, v170
	v_and_b32_e32 v163, 0xffff0000, v170
	v_lshlrev_b32_e32 v164, 16, v171
	v_and_b32_e32 v165, 0xffff0000, v171
	v_lshlrev_b32_e32 v154, 16, v172
	v_and_b32_e32 v155, 0xffff0000, v172
	v_lshlrev_b32_e32 v156, 16, v173
	v_and_b32_e32 v157, 0xffff0000, v173
	v_rcp_f32_e32 v134, v134
	v_rcp_f32_e32 v135, v135
	v_rcp_f32_e32 v136, v136
	v_rcp_f32_e32 v137, v137
	v_rcp_f32_e32 v126, v126
	v_rcp_f32_e32 v127, v127
	v_rcp_f32_e32 v128, v128
	v_rcp_f32_e32 v129, v129
	v_mul_f32_e32 v110, 0xbfb8aa3b, v110
	v_mul_f32_e32 v111, 0xbfb8aa3b, v111
	v_mul_f32_e32 v112, 0xbfb8aa3b, v112
	v_mul_f32_e32 v113, 0xbfb8aa3b, v113
	v_mul_f32_e32 v106, 0xbfb8aa3b, v106
	v_mul_f32_e32 v107, 0xbfb8aa3b, v107
	v_mul_f32_e32 v108, 0xbfb8aa3b, v108
	v_mul_f32_e32 v109, 0xbfb8aa3b, v109
	v_pk_mul_f32 v[144:145], v[144:145], v[164:165]
	v_pk_mul_f32 v[142:143], v[142:143], v[162:163]
	v_pk_mul_f32 v[156:157], v[140:141], v[156:157]
	v_pk_mul_f32 v[140:141], v[138:139], v[154:155]
	v_exp_f32_e32 v110, v110
	v_exp_f32_e32 v111, v111
	v_exp_f32_e32 v112, v112
	v_exp_f32_e32 v113, v113
	v_exp_f32_e32 v106, v106
	v_exp_f32_e32 v107, v107
	v_exp_f32_e32 v108, v108
	v_exp_f32_e32 v109, v109
	v_cvt_pk_bf16_f32 v138, v142, v143
	v_cvt_pk_bf16_f32 v139, v144, v145
	v_cvt_pk_bf16_f32 v140, v140, v141
	v_cvt_pk_bf16_f32 v141, v156, v157
	v_add_f32_e32 v118, 1.0, v118
	v_add_f32_e32 v119, 1.0, v119
	v_add_f32_e32 v120, 1.0, v120
	v_add_f32_e32 v121, 1.0, v121
	v_add_f32_e32 v114, 1.0, v114
	v_add_f32_e32 v115, 1.0, v115
	v_add_f32_e32 v116, 1.0, v116
	v_add_f32_e32 v117, 1.0, v117
	v_pk_add_f32 v[104:105], v[104:105], v[48:49]
	v_pk_add_f32 v[102:103], v[102:103], v[46:47]
	v_pk_add_f32 v[100:101], v[100:101], v[40:41]
	v_pk_add_f32 v[98:99], v[98:99], v[38:39]
	global_store_dwordx4 v[190:191], v[138:141], off offset:1280
	s_waitcnt vmcnt(7)
; __device__ __forceinline__ u32x4 pack8(const f32x4 a, const f32x4 b) { u32x4 w; w.x = cvt_pk_bf16(a[0], a[1]); w.y = cvt_pk_bf16(a[2], a[3]); w.z = cvt_pk_bf16(b[0], b[1]); w.w = cvt_pk_bf16(b[2], b[3]); return w; }
; __device__ __forceinline__ void unpack8(const u32x4 w, f32x4& a, f32x4& b) { a = (f32x4){bflo(w.x), bfhi(w.x), bflo(w.y), bfhi(w.y)}; b = (f32x4){bflo(w.z), bfhi(w.z), bflo(w.w), bfhi(w.w)}; }
; __device__ __forceinline__ f32x4 sig4(const f32x4 v) { return (f32x4){sigmoidf_(v[0]), sigmoidf_(v[1]), sigmoidf_(v[2]), sigmoidf_(v[3])}; }
;     __device__ __forceinline__ void operator()(const Acc& acc, const Unit& u, int wr, int wc, int fr, int fq) const {
;     ...
;         for (int ai = 0; ai < 2; ++ai) {
;             u32x4 av[4][2];
; #pragma unroll
;             for (int m = 0; m < 4; ++m)
; #pragma unroll
;                 for (int bj = 0; bj < 2; ++bj) av[m][bj] = *(const u32x4*)(proj + (size_t)(row0 + ai * 128 + m * 16) * NPROJ + col0 + bj * 128);
; #pragma unroll
;             for (int m = 0; m < 4; ++m) { bf16_t* rowp = proj + (size_t)(row0 + ai * 128 + m * 16) * NPROJ + col0;
; #pragma unroll
;                 for (int bj = 0; bj < 2; ++bj) { f32x4 a0, a1; unpack8(av[m][bj], a0, a1);
;                     const f32x4 o0 = a0 * sig4(acc[ai][bj][m][0] + bv[bj][0]), o1 = a1 * sig4(acc[ai][bj][m][1] + bv[bj][1]);
;                     *(u32x4*)(rowp + C_GLU + bj * 128) = pack8(o0, o1); } } }
	v_lshlrev_b32_e32 v142, 16, v167
	v_and_b32_e32 v143, 0xffff0000, v167
	v_lshlrev_b32_e32 v140, 16, v166
	v_and_b32_e32 v141, 0xffff0000, v166
	v_lshlrev_b32_e32 v144, 16, v168
	v_and_b32_e32 v145, 0xffff0000, v168
	v_lshlrev_b32_e32 v154, 16, v169
	v_and_b32_e32 v155, 0xffff0000, v169
	v_rcp_f32_e32 v118, v118
	v_rcp_f32_e32 v119, v119
	v_rcp_f32_e32 v120, v120
	v_rcp_f32_e32 v121, v121
	v_rcp_f32_e32 v114, v114
	v_rcp_f32_e32 v115, v115
	v_rcp_f32_e32 v116, v116
	v_rcp_f32_e32 v117, v117
	v_mul_f32_e32 v102, 0xbfb8aa3b, v102
	v_mul_f32_e32 v103, 0xbfb8aa3b, v103
	v_mul_f32_e32 v104, 0xbfb8aa3b, v104
	v_mul_f32_e32 v105, 0xbfb8aa3b, v105
	v_mul_f32_e32 v98, 0xbfb8aa3b, v98
	v_mul_f32_e32 v99, 0xbfb8aa3b, v99
	v_mul_f32_e32 v100, 0xbfb8aa3b, v100
	v_mul_f32_e32 v101, 0xbfb8aa3b, v101
	v_mad_i64_i32 v[138:139], s[42:43], v209, s96, v[186:187]
	v_pk_mul_f32 v[136:137], v[136:137], v[142:143]
	v_pk_mul_f32 v[134:135], v[134:135], v[140:141]
	v_pk_mul_f32 v[140:141], v[128:129], v[154:155]
	v_pk_mul_f32 v[128:129], v[126:127], v[144:145]
	v_exp_f32_e32 v102, v102
	v_exp_f32_e32 v103, v103
	v_exp_f32_e32 v104, v104
	v_exp_f32_e32 v105, v105
	v_exp_f32_e32 v98, v98
	v_exp_f32_e32 v99, v99
	v_exp_f32_e32 v100, v100
	v_exp_f32_e32 v101, v101
	v_lshl_add_u64 v[138:139], v[138:139], 0, v[184:185]
	v_cvt_pk_bf16_f32 v126, v134, v135
	v_cvt_pk_bf16_f32 v127, v136, v137
	v_cvt_pk_bf16_f32 v128, v128, v129
	v_cvt_pk_bf16_f32 v129, v140, v141
	v_add_f32_e32 v110, 1.0, v110
	v_add_f32_e32 v111, 1.0, v111
	v_add_f32_e32 v112, 1.0, v112
	v_add_f32_e32 v113, 1.0, v113
	v_add_f32_e32 v106, 1.0, v106
	v_add_f32_e32 v107, 1.0, v107
	v_add_f32_e32 v108, 1.0, v108
	v_add_f32_e32 v109, 1.0, v109
	v_pk_add_f32 v[96:97], v[96:97], v[64:65]
	v_pk_add_f32 v[94:95], v[94:95], v[62:63]
	v_pk_add_f32 v[92:93], v[92:93], v[56:57]
	v_pk_add_f32 v[90:91], v[90:91], v[54:55]
	global_store_dwordx4 v[138:139], v[126:129], off offset:1024
	s_waitcnt vmcnt(7)
	v_lshlrev_b32_e32 v134, 16, v160
	v_and_b32_e32 v135, 0xffff0000, v160
	v_lshlrev_b32_e32 v126, 16, v158
	v_and_b32_e32 v127, 0xffff0000, v158
	v_lshlrev_b32_e32 v128, 16, v159
	v_and_b32_e32 v129, 0xffff0000, v159
	v_lshlrev_b32_e32 v136, 16, v161
	v_and_b32_e32 v137, 0xffff0000, v161
	v_rcp_f32_e32 v110, v110
	v_rcp_f32_e32 v111, v111
	v_rcp_f32_e32 v112, v112
	v_rcp_f32_e32 v113, v113
	v_rcp_f32_e32 v106, v106
	v_rcp_f32_e32 v107, v107
	v_rcp_f32_e32 v108, v108
	v_rcp_f32_e32 v109, v109
	v_mul_f32_e32 v94, 0xbfb8aa3b, v94
	v_mul_f32_e32 v95, 0xbfb8aa3b, v95
	v_mul_f32_e32 v96, 0xbfb8aa3b, v96
	v_mul_f32_e32 v97, 0xbfb8aa3b, v97
	v_mul_f32_e32 v90, 0xbfb8aa3b, v90
	v_mul_f32_e32 v91, 0xbfb8aa3b, v91
	v_mul_f32_e32 v92, 0xbfb8aa3b, v92
	v_mul_f32_e32 v93, 0xbfb8aa3b, v93
	v_pk_mul_f32 v[120:121], v[120:121], v[128:129]
	v_pk_mul_f32 v[118:119], v[118:119], v[126:127]
	v_pk_mul_f32 v[126:127], v[116:117], v[136:137]
	v_pk_mul_f32 v[116:117], v[114:115], v[134:135]
	v_exp_f32_e32 v94, v94
	v_exp_f32_e32 v95, v95
	v_exp_f32_e32 v96, v96
	v_exp_f32_e32 v97, v97
	v_exp_f32_e32 v90, v90
	v_exp_f32_e32 v91, v91
	v_exp_f32_e32 v92, v92
	v_exp_f32_e32 v93, v93
	v_cvt_pk_bf16_f32 v114, v118, v119
	v_cvt_pk_bf16_f32 v115, v120, v121
	v_cvt_pk_bf16_f32 v116, v116, v117
	v_cvt_pk_bf16_f32 v117, v126, v127
	v_add_f32_e32 v102, 1.0, v102
	v_add_f32_e32 v103, 1.0, v103
	v_add_f32_e32 v104, 1.0, v104
	v_add_f32_e32 v105, 1.0, v105
	v_add_f32_e32 v98, 1.0, v98
	v_add_f32_e32 v99, 1.0, v99
	v_add_f32_e32 v100, 1.0, v100
	v_add_f32_e32 v101, 1.0, v101
	v_pk_add_f32 v[88:89], v[88:89], v[48:49]
	v_pk_add_f32 v[86:87], v[86:87], v[46:47]
	v_pk_add_f32 v[84:85], v[84:85], v[40:41]
	v_pk_add_f32 v[82:83], v[82:83], v[38:39]
	global_store_dwordx4 v[138:139], v[114:117], off offset:1280
	s_waitcnt vmcnt(7)
	v_lshlrev_b32_e32 v118, 16, v151
	v_and_b32_e32 v119, 0xffff0000, v151
	v_lshlrev_b32_e32 v116, 16, v150
	v_and_b32_e32 v117, 0xffff0000, v150
	v_lshlrev_b32_e32 v120, 16, v152
	v_and_b32_e32 v121, 0xffff0000, v152
	v_lshlrev_b32_e32 v126, 16, v153
	v_and_b32_e32 v127, 0xffff0000, v153
	v_rcp_f32_e32 v102, v102
	v_rcp_f32_e32 v103, v103
	v_rcp_f32_e32 v104, v104
	v_rcp_f32_e32 v105, v105
	v_rcp_f32_e32 v98, v98
	v_rcp_f32_e32 v99, v99
	v_rcp_f32_e32 v100, v100
	v_rcp_f32_e32 v101, v101
	v_mul_f32_e32 v86, 0xbfb8aa3b, v86
	v_mul_f32_e32 v87, 0xbfb8aa3b, v87
	v_mul_f32_e32 v88, 0xbfb8aa3b, v88
	v_mul_f32_e32 v89, 0xbfb8aa3b, v89
	v_mul_f32_e32 v82, 0xbfb8aa3b, v82
	v_mul_f32_e32 v83, 0xbfb8aa3b, v83
	v_mul_f32_e32 v84, 0xbfb8aa3b, v84
	v_mul_f32_e32 v85, 0xbfb8aa3b, v85
	v_mad_i64_i32 v[114:115], s[42:43], v208, s96, v[186:187]
	v_pk_mul_f32 v[112:113], v[112:113], v[118:119]
	v_pk_mul_f32 v[110:111], v[110:111], v[116:117]
	v_pk_mul_f32 v[116:117], v[108:109], v[126:127]
	v_pk_mul_f32 v[108:109], v[106:107], v[120:121]
	v_exp_f32_e32 v86, v86
	v_exp_f32_e32 v87, v87
	v_exp_f32_e32 v88, v88
	v_exp_f32_e32 v89, v89
	v_exp_f32_e32 v82, v82
	v_exp_f32_e32 v83, v83
	v_exp_f32_e32 v84, v84
	v_exp_f32_e32 v85, v85
	v_lshl_add_u64 v[114:115], v[114:115], 0, v[184:185]
	v_cvt_pk_bf16_f32 v106, v110, v111
	v_cvt_pk_bf16_f32 v107, v112, v113
	v_cvt_pk_bf16_f32 v108, v108, v109
	v_cvt_pk_bf16_f32 v109, v116, v117
	v_add_f32_e32 v94, 1.0, v94
	v_add_f32_e32 v95, 1.0, v95
	v_add_f32_e32 v96, 1.0, v96
	v_add_f32_e32 v97, 1.0, v97
	v_add_f32_e32 v90, 1.0, v90
	v_add_f32_e32 v91, 1.0, v91
	v_add_f32_e32 v92, 1.0, v92
	v_add_f32_e32 v93, 1.0, v93
	global_store_dwordx4 v[114:115], v[106:109], off offset:1024
	s_waitcnt vmcnt(7)
; __device__ __forceinline__ u32x4 pack8(const f32x4 a, const f32x4 b) { u32x4 w; w.x = cvt_pk_bf16(a[0], a[1]); w.y = cvt_pk_bf16(a[2], a[3]); w.z = cvt_pk_bf16(b[0], b[1]); w.w = cvt_pk_bf16(b[2], b[3]); return w; }
; __device__ __forceinline__ void unpack8(const u32x4 w, f32x4& a, f32x4& b) { a = (f32x4){bflo(w.x), bfhi(w.x), bflo(w.y), bfhi(w.y)}; b = (f32x4){bflo(w.z), bfhi(w.z), bflo(w.w), bfhi(w.w)}; }
; __device__ __forceinline__ f32x4 sig4(const f32x4 v) { return (f32x4){sigmoidf_(v[0]), sigmoidf_(v[1]), sigmoidf_(v[2]), sigmoidf_(v[3])}; }
;     __device__ __forceinline__ void operator()(const Acc& acc, const Unit& u, int wr, int wc, int fr, int fq) const {
;     ...
;         for (int ai = 0; ai < 2; ++ai) {
;             u32x4 av[4][2];
; #pragma unroll
;             for (int m = 0; m < 4; ++m)
; #pragma unroll
;                 for (int bj = 0; bj < 2; ++bj) av[m][bj] = *(const u32x4*)(proj + (size_t)(row0 + ai * 128 + m * 16) * NPROJ + col0 + bj * 128);
; #pragma unroll
;             for (int m = 0; m < 4; ++m) { bf16_t* rowp = proj + (size_t)(row0 + ai * 128 + m * 16) * NPROJ + col0;
; #pragma unroll
;                 for (int bj = 0; bj < 2; ++bj) { f32x4 a0, a1; unpack8(av[m][bj], a0, a1);
;                     const f32x4 o0 = a0 * sig4(acc[ai][bj][m][0] + bv[bj][0]), o1 = a1 * sig4(acc[ai][bj][m][1] + bv[bj][1]);
;                     *(u32x4*)(rowp + C_GLU + bj * 128) = pack8(o0, o1); } } }
	v_lshlrev_b32_e32 v110, 16, v148
	v_and_b32_e32 v111, 0xffff0000, v148
	v_lshlrev_b32_e32 v106, 16, v146
	v_and_b32_e32 v107, 0xffff0000, v146
	v_lshlrev_b32_e32 v108, 16, v147
	v_and_b32_e32 v109, 0xffff0000, v147
	v_lshlrev_b32_e32 v112, 16, v149
	v_and_b32_e32 v113, 0xffff0000, v149
	v_rcp_f32_e32 v94, v94
	v_rcp_f32_e32 v95, v95
	v_rcp_f32_e32 v96, v96
	v_rcp_f32_e32 v97, v97
	v_rcp_f32_e32 v90, v90
	v_rcp_f32_e32 v91, v91
	v_rcp_f32_e32 v92, v92
	v_rcp_f32_e32 v93, v93
	v_pk_mul_f32 v[104:105], v[104:105], v[108:109]
	v_pk_mul_f32 v[102:103], v[102:103], v[106:107]
	v_pk_mul_f32 v[106:107], v[100:101], v[112:113]
	v_pk_mul_f32 v[100:101], v[98:99], v[110:111]
	v_cvt_pk_bf16_f32 v98, v102, v103
	v_cvt_pk_bf16_f32 v99, v104, v105
	v_cvt_pk_bf16_f32 v100, v100, v101
	v_cvt_pk_bf16_f32 v101, v106, v107
	v_add_f32_e32 v86, 1.0, v86
	v_add_f32_e32 v87, 1.0, v87
	v_add_f32_e32 v88, 1.0, v88
	v_add_f32_e32 v89, 1.0, v89
	v_add_f32_e32 v82, 1.0, v82
	v_add_f32_e32 v83, 1.0, v83
	v_add_f32_e32 v84, 1.0, v84
	v_add_f32_e32 v85, 1.0, v85
	global_store_dwordx4 v[114:115], v[98:101], off offset:1280
	s_waitcnt vmcnt(7)
	v_lshlrev_b32_e32 v102, 16, v131
	v_and_b32_e32 v103, 0xffff0000, v131
	v_lshlrev_b32_e32 v100, 16, v130
	v_and_b32_e32 v101, 0xffff0000, v130
	v_lshlrev_b32_e32 v104, 16, v132
	v_and_b32_e32 v105, 0xffff0000, v132
	v_lshlrev_b32_e32 v106, 16, v133
	v_and_b32_e32 v107, 0xffff0000, v133
	v_rcp_f32_e32 v86, v86
	v_rcp_f32_e32 v87, v87
	v_rcp_f32_e32 v88, v88
	v_rcp_f32_e32 v89, v89
	v_rcp_f32_e32 v82, v82
	v_rcp_f32_e32 v83, v83
	v_rcp_f32_e32 v84, v84
	v_rcp_f32_e32 v85, v85
	v_mad_i64_i32 v[98:99], s[42:43], v207, s96, v[186:187]
	v_pk_mul_f32 v[96:97], v[96:97], v[102:103]
	v_pk_mul_f32 v[94:95], v[94:95], v[100:101]
	v_pk_mul_f32 v[100:101], v[92:93], v[106:107]
	v_pk_mul_f32 v[92:93], v[90:91], v[104:105]
	v_lshl_add_u64 v[98:99], v[98:99], 0, v[184:185]
	v_cvt_pk_bf16_f32 v90, v94, v95
	v_cvt_pk_bf16_f32 v91, v96, v97
	v_cvt_pk_bf16_f32 v92, v92, v93
	v_cvt_pk_bf16_f32 v93, v100, v101
	global_store_dwordx4 v[98:99], v[90:93], off offset:1024
	s_waitcnt vmcnt(7)
	v_lshlrev_b32_e32 v94, 16, v124
	v_and_b32_e32 v95, 0xffff0000, v124
	v_lshlrev_b32_e32 v90, 16, v122
	v_and_b32_e32 v91, 0xffff0000, v122
	v_lshlrev_b32_e32 v92, 16, v123
	v_and_b32_e32 v93, 0xffff0000, v123
	v_lshlrev_b32_e32 v96, 16, v125
	v_and_b32_e32 v97, 0xffff0000, v125
	v_pk_mul_f32 v[88:89], v[88:89], v[92:93]
	v_pk_mul_f32 v[86:87], v[86:87], v[90:91]
	v_pk_mul_f32 v[90:91], v[84:85], v[96:97]
	v_pk_mul_f32 v[84:85], v[82:83], v[94:95]
	v_cvt_pk_bf16_f32 v82, v86, v87
	v_cvt_pk_bf16_f32 v83, v88, v89
	v_cvt_pk_bf16_f32 v84, v84, v85
	v_cvt_pk_bf16_f32 v85, v90, v91
	v_add_u32_e32 v110, 0x80, v206
	global_store_dwordx4 v[98:99], v[82:85], off offset:1280
	v_add_u32_e32 v122, 0x90, v206
	v_add_u32_e32 v113, 0xa0, v206
	v_mad_i64_i32 v[82:83], s[42:43], v110, s96, v[188:189]
	global_load_dwordx4 v[106:109], v[82:83], off
	global_load_dwordx4 v[114:117], v[82:83], off offset:256
	v_mad_i64_i32 v[82:83], s[42:43], v122, s96, v[188:189]
	global_load_dwordx4 v[102:105], v[82:83], off
	global_load_dwordx4 v[98:101], v[82:83], off offset:256
	v_mad_i64_i32 v[82:83], s[42:43], v113, s96, v[188:189]
	global_load_dwordx4 v[94:97], v[82:83], off
	global_load_dwordx4 v[90:93], v[82:83], off offset:256
	v_add_u32_e32 v112, 0xb0, v206
	v_mad_i64_i32 v[82:83], s[42:43], v112, s96, v[188:189]
	global_load_dwordx4 v[86:89], v[82:83], off
	s_nop 0
	global_load_dwordx4 v[82:85], v[82:83], off offset:256
	v_pk_add_f32 v[80:81], v[80:81], v[64:65]
	v_pk_add_f32 v[78:79], v[78:79], v[62:63]
	v_pk_add_f32 v[76:77], v[76:77], v[56:57]
	v_pk_add_f32 v[74:75], v[74:75], v[54:55]
	v_mul_f32_e32 v78, 0xbfb8aa3b, v78
	v_mul_f32_e32 v79, 0xbfb8aa3b, v79
	v_mul_f32_e32 v80, 0xbfb8aa3b, v80
	v_mul_f32_e32 v81, 0xbfb8aa3b, v81
	v_mul_f32_e32 v74, 0xbfb8aa3b, v74
	v_mul_f32_e32 v75, 0xbfb8aa3b, v75
	v_mul_f32_e32 v76, 0xbfb8aa3b, v76
	v_mul_f32_e32 v77, 0xbfb8aa3b, v77
	v_exp_f32_e32 v78, v78
	v_exp_f32_e32 v79, v79
	v_exp_f32_e32 v80, v80
	v_exp_f32_e32 v81, v81
	v_exp_f32_e32 v74, v74
	v_exp_f32_e32 v75, v75
	v_exp_f32_e32 v76, v76
	v_exp_f32_e32 v77, v77
	v_pk_add_f32 v[72:73], v[72:73], v[48:49]
	v_pk_add_f32 v[70:71], v[70:71], v[46:47]
	v_pk_add_f32 v[68:69], v[68:69], v[40:41]
	v_pk_add_f32 v[66:67], v[66:67], v[38:39]
	v_mul_f32_e32 v70, 0xbfb8aa3b, v70
	v_mul_f32_e32 v71, 0xbfb8aa3b, v71
	v_mul_f32_e32 v72, 0xbfb8aa3b, v72
	v_mul_f32_e32 v73, 0xbfb8aa3b, v73
	v_mul_f32_e32 v66, 0xbfb8aa3b, v66
	v_mul_f32_e32 v67, 0xbfb8aa3b, v67
	v_mul_f32_e32 v68, 0xbfb8aa3b, v68
	v_mul_f32_e32 v69, 0xbfb8aa3b, v69
	v_exp_f32_e32 v70, v70
	v_exp_f32_e32 v71, v71
	v_exp_f32_e32 v72, v72
	v_exp_f32_e32 v73, v73
	v_exp_f32_e32 v66, v66
	v_exp_f32_e32 v67, v67
	v_exp_f32_e32 v68, v68
	v_exp_f32_e32 v69, v69
	v_add_f32_e32 v78, 1.0, v78
	v_add_f32_e32 v79, 1.0, v79
	v_add_f32_e32 v80, 1.0, v80
	v_add_f32_e32 v81, 1.0, v81
	v_add_f32_e32 v74, 1.0, v74
	v_add_f32_e32 v75, 1.0, v75
	v_add_f32_e32 v76, 1.0, v76
	v_add_f32_e32 v77, 1.0, v77
	v_pk_add_f32 v[60:61], v[60:61], v[64:65]
	v_pk_add_f32 v[58:59], v[58:59], v[62:63]
	v_pk_add_f32 v[52:53], v[52:53], v[56:57]
	v_pk_add_f32 v[50:51], v[50:51], v[54:55]
	v_rcp_f32_e32 v78, v78
	v_rcp_f32_e32 v79, v79
	v_rcp_f32_e32 v80, v80
	v_rcp_f32_e32 v81, v81
	v_rcp_f32_e32 v74, v74
	v_rcp_f32_e32 v75, v75
	v_rcp_f32_e32 v76, v76
	v_rcp_f32_e32 v77, v77
	v_mul_f32_e32 v58, 0xbfb8aa3b, v58
	v_mul_f32_e32 v59, 0xbfb8aa3b, v59
	v_mul_f32_e32 v60, 0xbfb8aa3b, v60
	v_mul_f32_e32 v61, 0xbfb8aa3b, v61
	v_mul_f32_e32 v50, 0xbfb8aa3b, v50
	v_mul_f32_e32 v51, 0xbfb8aa3b, v51
	v_mul_f32_e32 v52, 0xbfb8aa3b, v52
	v_mul_f32_e32 v53, 0xbfb8aa3b, v53
	v_exp_f32_e32 v58, v58
	v_exp_f32_e32 v59, v59
	v_exp_f32_e32 v60, v60
	v_exp_f32_e32 v61, v61
	v_exp_f32_e32 v50, v50
	v_exp_f32_e32 v51, v51
	v_exp_f32_e32 v52, v52
	v_exp_f32_e32 v53, v53
	v_add_f32_e32 v70, 1.0, v70
	v_add_f32_e32 v71, 1.0, v71
	v_add_f32_e32 v72, 1.0, v72
	v_add_f32_e32 v73, 1.0, v73
	v_add_f32_e32 v66, 1.0, v66
	v_add_f32_e32 v67, 1.0, v67
	v_add_f32_e32 v68, 1.0, v68
	v_add_f32_e32 v69, 1.0, v69
	v_pk_add_f32 v[44:45], v[44:45], v[48:49]
	v_pk_add_f32 v[42:43], v[42:43], v[46:47]
	v_pk_add_f32 v[36:37], v[36:37], v[40:41]
	v_pk_add_f32 v[34:35], v[34:35], v[38:39]
	s_waitcnt vmcnt(7)
; __device__ __forceinline__ u32x4 pack8(const f32x4 a, const f32x4 b) { u32x4 w; w.x = cvt_pk_bf16(a[0], a[1]); w.y = cvt_pk_bf16(a[2], a[3]); w.z = cvt_pk_bf16(b[0], b[1]); w.w = cvt_pk_bf16(b[2], b[3]); return w; }
; __device__ __forceinline__ void unpack8(const u32x4 w, f32x4& a, f32x4& b) { a = (f32x4){bflo(w.x), bfhi(w.x), bflo(w.y), bfhi(w.y)}; b = (f32x4){bflo(w.z), bfhi(w.z), bflo(w.w), bfhi(w.w)}; }
; __device__ __forceinline__ f32x4 sig4(const f32x4 v) { return (f32x4){sigmoidf_(v[0]), sigmoidf_(v[1]), sigmoidf_(v[2]), sigmoidf_(v[3])}; }
;     __device__ __forceinline__ void operator()(const Acc& acc, const Unit& u, int wr, int wc, int fr, int fq) const {
;     ...
;         for (int ai = 0; ai < 2; ++ai) {
;             u32x4 av[4][2];
; #pragma unroll
;             for (int m = 0; m < 4; ++m)
; #pragma unroll
;                 for (int bj = 0; bj < 2; ++bj) av[m][bj] = *(const u32x4*)(proj + (size_t)(row0 + ai * 128 + m * 16) * NPROJ + col0 + bj * 128);
; #pragma unroll
;             for (int m = 0; m < 4; ++m) { bf16_t* rowp = proj + (size_t)(row0 + ai * 128 + m * 16) * NPROJ + col0;
; #pragma unroll
;                 for (int bj = 0; bj < 2; ++bj) { f32x4 a0, a1; unpack8(av[m][bj], a0, a1);
;                     const f32x4 o0 = a0 * sig4(acc[ai][bj][m][0] + bv[bj][0]), o1 = a1 * sig4(acc[ai][bj][m][1] + bv[bj][1]);
;                     *(u32x4*)(rowp + C_GLU + bj * 128) = pack8(o0, o1); } } }
	v_lshlrev_b32_e32 v118, 16, v106
	v_and_b32_e32 v119, 0xffff0000, v106
	v_lshlrev_b32_e32 v106, 16, v107
	v_and_b32_e32 v107, 0xffff0000, v107
	v_lshlrev_b32_e32 v120, 16, v108
	v_and_b32_e32 v121, 0xffff0000, v108
	v_lshlrev_b32_e32 v108, 16, v109
	v_and_b32_e32 v109, 0xffff0000, v109
	v_rcp_f32_e32 v70, v70
	v_rcp_f32_e32 v71, v71
	v_rcp_f32_e32 v72, v72
	v_rcp_f32_e32 v73, v73
	v_rcp_f32_e32 v66, v66
	v_rcp_f32_e32 v67, v67
	v_rcp_f32_e32 v68, v68
	v_rcp_f32_e32 v69, v69
	v_mul_f32_e32 v42, 0xbfb8aa3b, v42
	v_mul_f32_e32 v43, 0xbfb8aa3b, v43
	v_mul_f32_e32 v44, 0xbfb8aa3b, v44
	v_mul_f32_e32 v45, 0xbfb8aa3b, v45
	v_mul_f32_e32 v34, 0xbfb8aa3b, v34
	v_mul_f32_e32 v35, 0xbfb8aa3b, v35
	v_mul_f32_e32 v36, 0xbfb8aa3b, v36
	v_mul_f32_e32 v37, 0xbfb8aa3b, v37
	v_mad_i64_i32 v[110:111], s[42:43], v110, s96, v[186:187]
	v_pk_mul_f32 v[80:81], v[80:81], v[106:107]
	v_pk_mul_f32 v[78:79], v[78:79], v[118:119]
	v_pk_mul_f32 v[106:107], v[76:77], v[108:109]
	v_pk_mul_f32 v[76:77], v[74:75], v[120:121]
	v_exp_f32_e32 v42, v42
	v_exp_f32_e32 v43, v43
	v_exp_f32_e32 v44, v44
	v_exp_f32_e32 v45, v45
	v_exp_f32_e32 v34, v34
	v_exp_f32_e32 v35, v35
	v_exp_f32_e32 v36, v36
	v_exp_f32_e32 v37, v37
	v_lshl_add_u64 v[110:111], v[110:111], 0, v[184:185]
	v_cvt_pk_bf16_f32 v74, v78, v79
	v_cvt_pk_bf16_f32 v75, v80, v81
	v_cvt_pk_bf16_f32 v76, v76, v77
	v_cvt_pk_bf16_f32 v77, v106, v107
	v_add_f32_e32 v58, 1.0, v58
	v_add_f32_e32 v59, 1.0, v59
	v_add_f32_e32 v60, 1.0, v60
	v_add_f32_e32 v61, 1.0, v61
	v_add_f32_e32 v50, 1.0, v50
	v_add_f32_e32 v51, 1.0, v51
	v_add_f32_e32 v52, 1.0, v52
	v_add_f32_e32 v53, 1.0, v53
	v_pk_add_f32 v[32:33], v[32:33], v[64:65]
	v_pk_add_f32 v[30:31], v[30:31], v[62:63]
	v_pk_add_f32 v[28:29], v[28:29], v[56:57]
	v_pk_add_f32 v[26:27], v[26:27], v[54:55]
	global_store_dwordx4 v[110:111], v[74:77], off offset:1024
	s_waitcnt vmcnt(7)
	v_lshlrev_b32_e32 v78, 16, v116
	v_and_b32_e32 v79, 0xffff0000, v116
	v_lshlrev_b32_e32 v74, 16, v114
	v_and_b32_e32 v75, 0xffff0000, v114
	v_lshlrev_b32_e32 v76, 16, v115
	v_and_b32_e32 v77, 0xffff0000, v115
	v_lshlrev_b32_e32 v80, 16, v117
	v_and_b32_e32 v81, 0xffff0000, v117
	v_rcp_f32_e32 v58, v58
	v_rcp_f32_e32 v59, v59
	v_rcp_f32_e32 v60, v60
	v_rcp_f32_e32 v61, v61
	v_rcp_f32_e32 v50, v50
	v_rcp_f32_e32 v51, v51
	v_rcp_f32_e32 v52, v52
	v_rcp_f32_e32 v53, v53
	v_mul_f32_e32 v30, 0xbfb8aa3b, v30
	v_mul_f32_e32 v31, 0xbfb8aa3b, v31
	v_mul_f32_e32 v32, 0xbfb8aa3b, v32
	v_mul_f32_e32 v33, 0xbfb8aa3b, v33
	v_mul_f32_e32 v26, 0xbfb8aa3b, v26
	v_mul_f32_e32 v27, 0xbfb8aa3b, v27
	v_mul_f32_e32 v28, 0xbfb8aa3b, v28
	v_mul_f32_e32 v29, 0xbfb8aa3b, v29
	v_pk_mul_f32 v[72:73], v[72:73], v[76:77]
	v_pk_mul_f32 v[70:71], v[70:71], v[74:75]
	v_pk_mul_f32 v[74:75], v[68:69], v[80:81]
	v_pk_mul_f32 v[68:69], v[66:67], v[78:79]
	v_exp_f32_e32 v30, v30
	v_exp_f32_e32 v31, v31
	v_exp_f32_e32 v32, v32
	v_exp_f32_e32 v33, v33
	v_exp_f32_e32 v26, v26
	v_exp_f32_e32 v27, v27
	v_exp_f32_e32 v28, v28
	v_exp_f32_e32 v29, v29
	v_cvt_pk_bf16_f32 v66, v70, v71
	v_cvt_pk_bf16_f32 v67, v72, v73
	v_cvt_pk_bf16_f32 v68, v68, v69
	v_cvt_pk_bf16_f32 v69, v74, v75
	v_add_f32_e32 v42, 1.0, v42
	v_add_f32_e32 v43, 1.0, v43
	v_add_f32_e32 v44, 1.0, v44
	v_add_f32_e32 v45, 1.0, v45
	v_add_f32_e32 v34, 1.0, v34
	v_add_f32_e32 v35, 1.0, v35
	v_add_f32_e32 v36, 1.0, v36
	v_add_f32_e32 v37, 1.0, v37
	v_pk_add_f32 v[24:25], v[24:25], v[48:49]
	v_pk_add_f32 v[22:23], v[22:23], v[46:47]
	v_pk_add_f32 v[20:21], v[20:21], v[40:41]
	v_pk_add_f32 v[18:19], v[18:19], v[38:39]
	global_store_dwordx4 v[110:111], v[66:69], off offset:1280
	s_waitcnt vmcnt(7)
	v_lshlrev_b32_e32 v70, 16, v103
	v_and_b32_e32 v71, 0xffff0000, v103
	v_lshlrev_b32_e32 v68, 16, v102
	v_and_b32_e32 v69, 0xffff0000, v102
	v_lshlrev_b32_e32 v72, 16, v104
	v_and_b32_e32 v73, 0xffff0000, v104
	v_lshlrev_b32_e32 v74, 16, v105
	v_and_b32_e32 v75, 0xffff0000, v105
	v_rcp_f32_e32 v42, v42
	v_rcp_f32_e32 v43, v43
	v_rcp_f32_e32 v44, v44
	v_rcp_f32_e32 v45, v45
	v_rcp_f32_e32 v34, v34
	v_rcp_f32_e32 v35, v35
	v_rcp_f32_e32 v36, v36
	v_rcp_f32_e32 v37, v37
	v_mul_f32_e32 v22, 0xbfb8aa3b, v22
	v_mul_f32_e32 v23, 0xbfb8aa3b, v23
	v_mul_f32_e32 v24, 0xbfb8aa3b, v24
	v_mul_f32_e32 v25, 0xbfb8aa3b, v25
	v_mul_f32_e32 v18, 0xbfb8aa3b, v18
	v_mul_f32_e32 v19, 0xbfb8aa3b, v19
	v_mul_f32_e32 v20, 0xbfb8aa3b, v20
	v_mul_f32_e32 v21, 0xbfb8aa3b, v21
	v_mad_i64_i32 v[66:67], s[42:43], v122, s96, v[186:187]
	v_pk_mul_f32 v[60:61], v[60:61], v[70:71]
	v_pk_mul_f32 v[58:59], v[58:59], v[68:69]
	v_pk_mul_f32 v[68:69], v[52:53], v[74:75]
	v_pk_mul_f32 v[52:53], v[50:51], v[72:73]
	v_exp_f32_e32 v22, v22
	v_exp_f32_e32 v23, v23
	v_exp_f32_e32 v24, v24
	v_exp_f32_e32 v25, v25
	v_exp_f32_e32 v18, v18
	v_exp_f32_e32 v19, v19
	v_exp_f32_e32 v20, v20
	v_exp_f32_e32 v21, v21
	v_lshl_add_u64 v[66:67], v[66:67], 0, v[184:185]
	v_cvt_pk_bf16_f32 v50, v58, v59
	v_cvt_pk_bf16_f32 v51, v60, v61
	v_cvt_pk_bf16_f32 v52, v52, v53
	v_cvt_pk_bf16_f32 v53, v68, v69
	v_add_f32_e32 v30, 1.0, v30
	v_add_f32_e32 v31, 1.0, v31
	v_add_f32_e32 v32, 1.0, v32
	v_add_f32_e32 v33, 1.0, v33
	v_add_f32_e32 v26, 1.0, v26
	v_add_f32_e32 v27, 1.0, v27
	v_add_f32_e32 v28, 1.0, v28
	v_add_f32_e32 v29, 1.0, v29
	v_pk_add_f32 v[16:17], v[16:17], v[64:65]
	v_pk_add_f32 v[14:15], v[14:15], v[62:63]
	v_pk_add_f32 v[12:13], v[12:13], v[56:57]
	v_pk_add_f32 v[10:11], v[10:11], v[54:55]
	global_store_dwordx4 v[66:67], v[50:53], off offset:1024
	s_waitcnt vmcnt(7)
; __device__ __forceinline__ u32x4 pack8(const f32x4 a, const f32x4 b) { u32x4 w; w.x = cvt_pk_bf16(a[0], a[1]); w.y = cvt_pk_bf16(a[2], a[3]); w.z = cvt_pk_bf16(b[0], b[1]); w.w = cvt_pk_bf16(b[2], b[3]); return w; }
; __device__ __forceinline__ void unpack8(const u32x4 w, f32x4& a, f32x4& b) { a = (f32x4){bflo(w.x), bfhi(w.x), bflo(w.y), bfhi(w.y)}; b = (f32x4){bflo(w.z), bfhi(w.z), bflo(w.w), bfhi(w.w)}; }
; __device__ __forceinline__ f32x4 sig4(const f32x4 v) { return (f32x4){sigmoidf_(v[0]), sigmoidf_(v[1]), sigmoidf_(v[2]), sigmoidf_(v[3])}; }
;     __device__ __forceinline__ void operator()(const Acc& acc, const Unit& u, int wr, int wc, int fr, int fq) const {
;     ...
;         for (int ai = 0; ai < 2; ++ai) {
;             u32x4 av[4][2];
; #pragma unroll
;             for (int m = 0; m < 4; ++m)
; #pragma unroll
;                 for (int bj = 0; bj < 2; ++bj) av[m][bj] = *(const u32x4*)(proj + (size_t)(row0 + ai * 128 + m * 16) * NPROJ + col0 + bj * 128);
; #pragma unroll
;             for (int m = 0; m < 4; ++m) { bf16_t* rowp = proj + (size_t)(row0 + ai * 128 + m * 16) * NPROJ + col0;
; #pragma unroll
;                 for (int bj = 0; bj < 2; ++bj) { f32x4 a0, a1; unpack8(av[m][bj], a0, a1);
;                     const f32x4 o0 = a0 * sig4(acc[ai][bj][m][0] + bv[bj][0]), o1 = a1 * sig4(acc[ai][bj][m][1] + bv[bj][1]);
;                     *(u32x4*)(rowp + C_GLU + bj * 128) = pack8(o0, o1); } } }
	v_lshlrev_b32_e32 v58, 16, v100
	v_and_b32_e32 v59, 0xffff0000, v100
	v_lshlrev_b32_e32 v50, 16, v98
	v_and_b32_e32 v51, 0xffff0000, v98
	v_lshlrev_b32_e32 v52, 16, v99
	v_and_b32_e32 v53, 0xffff0000, v99
	v_lshlrev_b32_e32 v60, 16, v101
	v_and_b32_e32 v61, 0xffff0000, v101
	v_rcp_f32_e32 v30, v30
	v_rcp_f32_e32 v31, v31
	v_rcp_f32_e32 v32, v32
	v_rcp_f32_e32 v33, v33
	v_rcp_f32_e32 v26, v26
	v_rcp_f32_e32 v27, v27
	v_rcp_f32_e32 v28, v28
	v_rcp_f32_e32 v29, v29
	v_mul_f32_e32 v14, 0xbfb8aa3b, v14
	v_mul_f32_e32 v15, 0xbfb8aa3b, v15
	v_mul_f32_e32 v16, 0xbfb8aa3b, v16
	v_mul_f32_e32 v17, 0xbfb8aa3b, v17
	v_mul_f32_e32 v10, 0xbfb8aa3b, v10
	v_mul_f32_e32 v11, 0xbfb8aa3b, v11
	v_mul_f32_e32 v12, 0xbfb8aa3b, v12
	v_mul_f32_e32 v13, 0xbfb8aa3b, v13
	v_pk_mul_f32 v[44:45], v[44:45], v[52:53]
	v_pk_mul_f32 v[42:43], v[42:43], v[50:51]
	v_pk_mul_f32 v[50:51], v[36:37], v[60:61]
	v_pk_mul_f32 v[36:37], v[34:35], v[58:59]
	v_exp_f32_e32 v14, v14
	v_exp_f32_e32 v15, v15
	v_exp_f32_e32 v16, v16
	v_exp_f32_e32 v17, v17
	v_exp_f32_e32 v10, v10
	v_exp_f32_e32 v11, v11
	v_exp_f32_e32 v12, v12
	v_exp_f32_e32 v13, v13
	v_cvt_pk_bf16_f32 v34, v42, v43
	v_cvt_pk_bf16_f32 v35, v44, v45
	v_cvt_pk_bf16_f32 v36, v36, v37
	v_cvt_pk_bf16_f32 v37, v50, v51
	v_add_f32_e32 v22, 1.0, v22
	v_add_f32_e32 v23, 1.0, v23
	v_add_f32_e32 v24, 1.0, v24
	v_add_f32_e32 v25, 1.0, v25
	v_add_f32_e32 v18, 1.0, v18
	v_add_f32_e32 v19, 1.0, v19
	v_add_f32_e32 v20, 1.0, v20
	v_add_f32_e32 v21, 1.0, v21
	v_pk_add_f32 v[8:9], v[8:9], v[48:49]
	v_pk_add_f32 v[6:7], v[6:7], v[46:47]
	v_pk_add_f32 v[4:5], v[4:5], v[40:41]
	v_pk_add_f32 v[2:3], v[2:3], v[38:39]
	global_store_dwordx4 v[66:67], v[34:37], off offset:1280
	s_waitcnt vmcnt(7)
	v_lshlrev_b32_e32 v42, 16, v95
	v_and_b32_e32 v43, 0xffff0000, v95
	v_lshlrev_b32_e32 v36, 16, v94
	v_and_b32_e32 v37, 0xffff0000, v94
	v_lshlrev_b32_e32 v44, 16, v96
	v_and_b32_e32 v45, 0xffff0000, v96
	v_lshlrev_b32_e32 v50, 16, v97
	v_and_b32_e32 v51, 0xffff0000, v97
	v_rcp_f32_e32 v22, v22
	v_rcp_f32_e32 v23, v23
	v_rcp_f32_e32 v24, v24
	v_rcp_f32_e32 v25, v25
	v_rcp_f32_e32 v18, v18
	v_rcp_f32_e32 v19, v19
	v_rcp_f32_e32 v20, v20
	v_rcp_f32_e32 v21, v21
	v_mul_f32_e32 v6, 0xbfb8aa3b, v6
	v_mul_f32_e32 v7, 0xbfb8aa3b, v7
	v_mul_f32_e32 v8, 0xbfb8aa3b, v8
	v_mul_f32_e32 v9, 0xbfb8aa3b, v9
	v_mul_f32_e32 v2, 0xbfb8aa3b, v2
	v_mul_f32_e32 v3, 0xbfb8aa3b, v3
	v_mul_f32_e32 v4, 0xbfb8aa3b, v4
	v_mul_f32_e32 v5, 0xbfb8aa3b, v5
	v_mad_i64_i32 v[34:35], s[42:43], v113, s96, v[186:187]
	v_pk_mul_f32 v[32:33], v[32:33], v[42:43]
	v_pk_mul_f32 v[30:31], v[30:31], v[36:37]
	v_pk_mul_f32 v[36:37], v[28:29], v[50:51]
	v_pk_mul_f32 v[28:29], v[26:27], v[44:45]
	v_exp_f32_e32 v6, v6
	v_exp_f32_e32 v7, v7
	v_exp_f32_e32 v8, v8
	v_exp_f32_e32 v9, v9
	v_exp_f32_e32 v2, v2
	v_exp_f32_e32 v3, v3
	v_exp_f32_e32 v4, v4
	v_exp_f32_e32 v5, v5
	v_lshl_add_u64 v[34:35], v[34:35], 0, v[184:185]
	v_cvt_pk_bf16_f32 v26, v30, v31
	v_cvt_pk_bf16_f32 v27, v32, v33
	v_cvt_pk_bf16_f32 v28, v28, v29
	v_cvt_pk_bf16_f32 v29, v36, v37
	v_add_f32_e32 v14, 1.0, v14
	v_add_f32_e32 v15, 1.0, v15
	v_add_f32_e32 v16, 1.0, v16
	v_add_f32_e32 v17, 1.0, v17
	v_add_f32_e32 v10, 1.0, v10
	v_add_f32_e32 v11, 1.0, v11
	v_add_f32_e32 v12, 1.0, v12
	v_add_f32_e32 v13, 1.0, v13
	global_store_dwordx4 v[34:35], v[26:29], off offset:1024
	s_waitcnt vmcnt(7)
	v_lshlrev_b32_e32 v30, 16, v92
	v_and_b32_e32 v31, 0xffff0000, v92
	v_lshlrev_b32_e32 v26, 16, v90
	v_and_b32_e32 v27, 0xffff0000, v90
	v_lshlrev_b32_e32 v28, 16, v91
	v_and_b32_e32 v29, 0xffff0000, v91
	v_lshlrev_b32_e32 v32, 16, v93
	v_and_b32_e32 v33, 0xffff0000, v93
	v_rcp_f32_e32 v14, v14
	v_rcp_f32_e32 v15, v15
	v_rcp_f32_e32 v16, v16
	v_rcp_f32_e32 v17, v17
	v_rcp_f32_e32 v10, v10
	v_rcp_f32_e32 v11, v11
	v_rcp_f32_e32 v12, v12
	v_rcp_f32_e32 v13, v13
	v_pk_mul_f32 v[24:25], v[24:25], v[28:29]
	v_pk_mul_f32 v[22:23], v[22:23], v[26:27]
	v_pk_mul_f32 v[26:27], v[20:21], v[32:33]
	v_pk_mul_f32 v[20:21], v[18:19], v[30:31]
	v_cvt_pk_bf16_f32 v18, v22, v23
	v_cvt_pk_bf16_f32 v19, v24, v25
	v_cvt_pk_bf16_f32 v20, v20, v21
	v_cvt_pk_bf16_f32 v21, v26, v27
	v_add_f32_e32 v6, 1.0, v6
	v_add_f32_e32 v7, 1.0, v7
	v_add_f32_e32 v8, 1.0, v8
	v_add_f32_e32 v9, 1.0, v9
	v_add_f32_e32 v2, 1.0, v2
	v_add_f32_e32 v3, 1.0, v3
	v_add_f32_e32 v4, 1.0, v4
	v_add_f32_e32 v5, 1.0, v5
	global_store_dwordx4 v[34:35], v[18:21], off offset:1280
	s_waitcnt vmcnt(7)
	v_lshlrev_b32_e32 v22, 16, v87
	v_and_b32_e32 v23, 0xffff0000, v87
	v_lshlrev_b32_e32 v20, 16, v86
	v_and_b32_e32 v21, 0xffff0000, v86
	v_lshlrev_b32_e32 v24, 16, v88
	v_and_b32_e32 v25, 0xffff0000, v88
	v_lshlrev_b32_e32 v26, 16, v89
	v_and_b32_e32 v27, 0xffff0000, v89
	v_rcp_f32_e32 v6, v6
	v_rcp_f32_e32 v7, v7
	v_rcp_f32_e32 v8, v8
	v_rcp_f32_e32 v9, v9
	v_rcp_f32_e32 v2, v2
	v_rcp_f32_e32 v3, v3
	v_rcp_f32_e32 v4, v4
	v_rcp_f32_e32 v5, v5
	v_mad_i64_i32 v[18:19], s[42:43], v112, s96, v[186:187]
	v_pk_mul_f32 v[16:17], v[16:17], v[22:23]
	v_pk_mul_f32 v[14:15], v[14:15], v[20:21]
	v_pk_mul_f32 v[20:21], v[12:13], v[26:27]
	v_pk_mul_f32 v[12:13], v[10:11], v[24:25]
	v_lshl_add_u64 v[18:19], v[18:19], 0, v[184:185]
	v_cvt_pk_bf16_f32 v10, v14, v15
	v_cvt_pk_bf16_f32 v11, v16, v17
	v_cvt_pk_bf16_f32 v12, v12, v13
	v_cvt_pk_bf16_f32 v13, v20, v21
	global_store_dwordx4 v[18:19], v[10:13], off offset:1024
	s_waitcnt vmcnt(7)
	v_lshlrev_b32_e32 v14, 16, v84
	v_and_b32_e32 v15, 0xffff0000, v84
	v_lshlrev_b32_e32 v10, 16, v82
	v_and_b32_e32 v11, 0xffff0000, v82
	v_lshlrev_b32_e32 v12, 16, v83
	v_and_b32_e32 v13, 0xffff0000, v83
	v_lshlrev_b32_e32 v16, 16, v85
	v_and_b32_e32 v17, 0xffff0000, v85
	v_pk_mul_f32 v[8:9], v[8:9], v[12:13]
	v_pk_mul_f32 v[6:7], v[6:7], v[10:11]
	v_pk_mul_f32 v[10:11], v[4:5], v[16:17]
	v_pk_mul_f32 v[4:5], v[2:3], v[14:15]
	v_cvt_pk_bf16_f32 v2, v6, v7
	v_cvt_pk_bf16_f32 v3, v8, v9
	v_cvt_pk_bf16_f32 v4, v4, v5
	v_cvt_pk_bf16_f32 v5, v10, v11
	global_store_dwordx4 v[18:19], v[2:5], off offset:1280
	s_cbranch_vccz .LBB0_378
	s_waitcnt vmcnt(0)
	s_cmpk_gt_u32 s29, 0xff
	s_cbranch_scc1 .LBB0_391
	s_barrier
